# P0 transposes: all 32 row loads of an item in flight (4 register sets) instead of 8
# baseline (speedup 1.0000x reference)
.LBB0_35:
	v_add_u32_e32 v63, s1, v4
	v_add_u32_e32 v14, 0xfcb20000, v63
	v_lshl_add_u64 v[6:7], v[14:15], 2, v[2:3]
	v_add_u32_e32 v14, 0xfcb21000, v63
	v_lshl_add_u64 v[8:9], v[14:15], 2, v[2:3]
	v_add_u32_e32 v14, 0xfcb22000, v63
	v_lshl_add_u64 v[10:11], v[14:15], 2, v[2:3]
	v_add_u32_e32 v14, 0xfcb23000, v63
	v_lshl_add_u64 v[12:13], v[14:15], 2, v[2:3]
	v_add_u32_e32 v14, 0xfcb24000, v63
	v_lshl_add_u64 v[64:65], v[14:15], 2, v[2:3]
	v_add_u32_e32 v14, 0xfcb25000, v63
	v_lshl_add_u64 v[66:67], v[14:15], 2, v[2:3]
	v_add_u32_e32 v14, 0xfcb26000, v63
	v_lshl_add_u64 v[68:69], v[14:15], 2, v[2:3]
	v_add_u32_e32 v14, 0xfcb27000, v63
	global_load_dwordx2 v[6:7], v[6:7], off
	s_nop 0
	global_load_dwordx2 v[8:9], v[8:9], off
	v_lshl_add_u64 v[70:71], v[14:15], 2, v[2:3]
	global_load_dwordx2 v[10:11], v[10:11], off
	s_nop 0
	global_load_dwordx2 v[12:13], v[12:13], off
	s_nop 0
	global_load_dwordx2 v[64:65], v[64:65], off
	s_nop 0
	global_load_dwordx2 v[66:67], v[66:67], off
	s_nop 0
	global_load_dwordx2 v[68:69], v[68:69], off
	s_nop 0
	global_load_dwordx2 v[70:71], v[70:71], off
	s_add_i32 s1, s1, 0x8000
	v_add_u32_e32 v63, s1, v4
	v_add_u32_e32 v14, 0xfcb20000, v63
	v_lshl_add_u64 v[150:151], v[14:15], 2, v[2:3]
	v_add_u32_e32 v14, 0xfcb21000, v63
	v_lshl_add_u64 v[152:153], v[14:15], 2, v[2:3]
	v_add_u32_e32 v14, 0xfcb22000, v63
	v_lshl_add_u64 v[154:155], v[14:15], 2, v[2:3]
	v_add_u32_e32 v14, 0xfcb23000, v63
	v_lshl_add_u64 v[156:157], v[14:15], 2, v[2:3]
	v_add_u32_e32 v14, 0xfcb24000, v63
	v_lshl_add_u64 v[158:159], v[14:15], 2, v[2:3]
	v_add_u32_e32 v14, 0xfcb25000, v63
	v_lshl_add_u64 v[160:161], v[14:15], 2, v[2:3]
	v_add_u32_e32 v14, 0xfcb26000, v63
	v_lshl_add_u64 v[162:163], v[14:15], 2, v[2:3]
	v_add_u32_e32 v14, 0xfcb27000, v63
	global_load_dwordx2 v[150:151], v[150:151], off
	s_nop 0
	global_load_dwordx2 v[152:153], v[152:153], off
	v_lshl_add_u64 v[164:165], v[14:15], 2, v[2:3]
	global_load_dwordx2 v[154:155], v[154:155], off
	s_nop 0
	global_load_dwordx2 v[156:157], v[156:157], off
	s_nop 0
	global_load_dwordx2 v[158:159], v[158:159], off
	s_nop 0
	global_load_dwordx2 v[160:161], v[160:161], off
	s_nop 0
	global_load_dwordx2 v[162:163], v[162:163], off
	s_nop 0
	global_load_dwordx2 v[164:165], v[164:165], off
	s_add_i32 s1, s1, 0x8000
	v_add_u32_e32 v63, s1, v4
	v_add_u32_e32 v14, 0xfcb20000, v63
	v_lshl_add_u64 v[166:167], v[14:15], 2, v[2:3]
	v_add_u32_e32 v14, 0xfcb21000, v63
	v_lshl_add_u64 v[168:169], v[14:15], 2, v[2:3]
	v_add_u32_e32 v14, 0xfcb22000, v63
	v_lshl_add_u64 v[170:171], v[14:15], 2, v[2:3]
	v_add_u32_e32 v14, 0xfcb23000, v63
	v_lshl_add_u64 v[172:173], v[14:15], 2, v[2:3]
	v_add_u32_e32 v14, 0xfcb24000, v63
	v_lshl_add_u64 v[174:175], v[14:15], 2, v[2:3]
	v_add_u32_e32 v14, 0xfcb25000, v63
	v_lshl_add_u64 v[176:177], v[14:15], 2, v[2:3]
	v_add_u32_e32 v14, 0xfcb26000, v63
	v_lshl_add_u64 v[178:179], v[14:15], 2, v[2:3]
	v_add_u32_e32 v14, 0xfcb27000, v63
	global_load_dwordx2 v[166:167], v[166:167], off
	s_nop 0
	global_load_dwordx2 v[168:169], v[168:169], off
	v_lshl_add_u64 v[180:181], v[14:15], 2, v[2:3]
	global_load_dwordx2 v[170:171], v[170:171], off
	s_nop 0
	global_load_dwordx2 v[172:173], v[172:173], off
	s_nop 0
	global_load_dwordx2 v[174:175], v[174:175], off
	s_nop 0
	global_load_dwordx2 v[176:177], v[176:177], off
	s_nop 0
	global_load_dwordx2 v[178:179], v[178:179], off
	s_nop 0
	global_load_dwordx2 v[180:181], v[180:181], off
	s_add_i32 s1, s1, 0x8000
	v_add_u32_e32 v63, s1, v4
	v_add_u32_e32 v14, 0xfcb20000, v63
	v_lshl_add_u64 v[182:183], v[14:15], 2, v[2:3]
	v_add_u32_e32 v14, 0xfcb21000, v63
	v_lshl_add_u64 v[184:185], v[14:15], 2, v[2:3]
	v_add_u32_e32 v14, 0xfcb22000, v63
	v_lshl_add_u64 v[186:187], v[14:15], 2, v[2:3]
	v_add_u32_e32 v14, 0xfcb23000, v63
	v_lshl_add_u64 v[188:189], v[14:15], 2, v[2:3]
	v_add_u32_e32 v14, 0xfcb24000, v63
	v_lshl_add_u64 v[190:191], v[14:15], 2, v[2:3]
	v_add_u32_e32 v14, 0xfcb25000, v63
	v_lshl_add_u64 v[192:193], v[14:15], 2, v[2:3]
	v_add_u32_e32 v14, 0xfcb26000, v63
	v_lshl_add_u64 v[194:195], v[14:15], 2, v[2:3]
	v_add_u32_e32 v14, 0xfcb27000, v63
	global_load_dwordx2 v[182:183], v[182:183], off
	s_nop 0
	global_load_dwordx2 v[184:185], v[184:185], off
	v_lshl_add_u64 v[196:197], v[14:15], 2, v[2:3]
	global_load_dwordx2 v[186:187], v[186:187], off
	s_nop 0
	global_load_dwordx2 v[188:189], v[188:189], off
	s_nop 0
	global_load_dwordx2 v[190:191], v[190:191], off
	s_nop 0
	global_load_dwordx2 v[192:193], v[192:193], off
	s_nop 0
	global_load_dwordx2 v[194:195], v[194:195], off
	s_nop 0
	global_load_dwordx2 v[196:197], v[196:197], off
	s_add_i32 s1, s1, 0x8000
	v_add_u32_e32 v14, 0x410, v5
	v_add_u32_e32 v63, 0x618, v5
	v_add_u32_e32 v72, 0x820, v5
	v_add_u32_e32 v73, 0xa28, v5
	v_add_u32_e32 v74, 0xc30, v5
	v_add_u32_e32 v75, 0xe38, v5
	s_waitcnt vmcnt(31)
	ds_write2_b32 v5, v6, v7 offset1:1
	s_waitcnt vmcnt(30)
	ds_write2_b32 v5, v8, v9 offset0:130 offset1:131
	v_add_u32_e32 v5, 0x1040, v5
	s_waitcnt vmcnt(29)
	ds_write2_b32 v14, v10, v11 offset1:1
	s_waitcnt vmcnt(28)
	ds_write2_b32 v63, v12, v13 offset1:1
	s_waitcnt vmcnt(27)
	ds_write2_b32 v72, v64, v65 offset1:1
	s_waitcnt vmcnt(26)
	ds_write2_b32 v73, v66, v67 offset1:1
	s_waitcnt vmcnt(25)
	ds_write2_b32 v74, v68, v69 offset1:1
	s_waitcnt vmcnt(24)
	ds_write2_b32 v75, v70, v71 offset1:1
	v_add_u32_e32 v14, 0x410, v5
	v_add_u32_e32 v63, 0x618, v5
	v_add_u32_e32 v72, 0x820, v5
	v_add_u32_e32 v73, 0xa28, v5
	v_add_u32_e32 v74, 0xc30, v5
	v_add_u32_e32 v75, 0xe38, v5
	s_waitcnt vmcnt(23)
	ds_write2_b32 v5, v150, v151 offset1:1
	s_waitcnt vmcnt(22)
	ds_write2_b32 v5, v152, v153 offset0:130 offset1:131
	v_add_u32_e32 v5, 0x1040, v5
	s_waitcnt vmcnt(21)
	ds_write2_b32 v14, v154, v155 offset1:1
	s_waitcnt vmcnt(20)
	ds_write2_b32 v63, v156, v157 offset1:1
	s_waitcnt vmcnt(19)
	ds_write2_b32 v72, v158, v159 offset1:1
	s_waitcnt vmcnt(18)
	ds_write2_b32 v73, v160, v161 offset1:1
	s_waitcnt vmcnt(17)
	ds_write2_b32 v74, v162, v163 offset1:1
	s_waitcnt vmcnt(16)
	ds_write2_b32 v75, v164, v165 offset1:1
	v_add_u32_e32 v14, 0x410, v5
	v_add_u32_e32 v63, 0x618, v5
	v_add_u32_e32 v72, 0x820, v5
	v_add_u32_e32 v73, 0xa28, v5
	v_add_u32_e32 v74, 0xc30, v5
	v_add_u32_e32 v75, 0xe38, v5
	s_waitcnt vmcnt(15)
	ds_write2_b32 v5, v166, v167 offset1:1
	s_waitcnt vmcnt(14)
	ds_write2_b32 v5, v168, v169 offset0:130 offset1:131
	v_add_u32_e32 v5, 0x1040, v5
	s_waitcnt vmcnt(13)
	ds_write2_b32 v14, v170, v171 offset1:1
	s_waitcnt vmcnt(12)
	ds_write2_b32 v63, v172, v173 offset1:1
	s_waitcnt vmcnt(11)
	ds_write2_b32 v72, v174, v175 offset1:1
	s_waitcnt vmcnt(10)
	ds_write2_b32 v73, v176, v177 offset1:1
	s_waitcnt vmcnt(9)
	ds_write2_b32 v74, v178, v179 offset1:1
	s_waitcnt vmcnt(8)
	ds_write2_b32 v75, v180, v181 offset1:1
	v_add_u32_e32 v14, 0x410, v5
	v_add_u32_e32 v63, 0x618, v5
	v_add_u32_e32 v72, 0x820, v5
	v_add_u32_e32 v73, 0xa28, v5
	v_add_u32_e32 v74, 0xc30, v5
	v_add_u32_e32 v75, 0xe38, v5
	s_waitcnt vmcnt(7)
	ds_write2_b32 v5, v182, v183 offset1:1
	s_waitcnt vmcnt(6)
	ds_write2_b32 v5, v184, v185 offset0:130 offset1:131
	v_add_u32_e32 v5, 0x1040, v5
	s_waitcnt vmcnt(5)
	ds_write2_b32 v14, v186, v187 offset1:1
	s_waitcnt vmcnt(4)
	ds_write2_b32 v63, v188, v189 offset1:1
	s_waitcnt vmcnt(3)
	ds_write2_b32 v72, v190, v191 offset1:1
	s_waitcnt vmcnt(2)
	ds_write2_b32 v73, v192, v193 offset1:1
	s_waitcnt vmcnt(1)
	ds_write2_b32 v74, v194, v195 offset1:1
	s_waitcnt vmcnt(0)
	ds_write2_b32 v75, v196, v197 offset1:1
	s_waitcnt lgkmcnt(0)
	ds_read2_b32 v[2:3], v81 offset1:65
	s_waitcnt lgkmcnt(0)
	v_cvt_pk_bf16_f32 v2, v2, v3
	ds_read2_b32 v[4:5], v81 offset0:130 offset1:195
	v_add_u32_e32 v12, 0x400, v81
	s_waitcnt lgkmcnt(0)
	v_cvt_pk_bf16_f32 v3, v4, v5
	ds_read2_b32 v[4:5], v12 offset0:4 offset1:69
	s_lshl_b32 s1, s96, 1
	s_waitcnt lgkmcnt(0)
	v_cvt_pk_bf16_f32 v4, v4, v5
	v_or_b32_e32 v5, s0, v80
	s_and_b32 s1, s1, 0x7fc0
	v_mul_u32_u24_e32 v8, 0x1600, v5
	s_add_i32 s8, s1, 0xffff9640
	v_lshlrev_b32_e32 v14, 1, v8
	v_lshl_add_u64 v[8:9], s[8:9], 1, v[22:23]
	v_lshl_add_u64 v[10:11], v[8:9], 0, v[14:15]
	ds_read2_b32 v[6:7], v12 offset0:134 offset1:199
	s_waitcnt lgkmcnt(0)
	v_cvt_pk_bf16_f32 v5, v6, v7
	global_store_dwordx4 v[10:11], v[2:5], off
	v_or_b32_e32 v10, s0, v82
	v_mul_u32_u24_e32 v10, 0x1600, v10
	ds_read2_b32 v[6:7], v81 offset0:8 offset1:73
	s_waitcnt lgkmcnt(0)
	v_cvt_pk_bf16_f32 v2, v6, v7
	ds_read2_b32 v[4:5], v81 offset0:138 offset1:203
	v_lshlrev_b32_e32 v14, 1, v10
	s_waitcnt lgkmcnt(0)
	v_cvt_pk_bf16_f32 v3, v4, v5
	ds_read2_b32 v[4:5], v12 offset0:12 offset1:77
	v_lshl_add_u64 v[10:11], v[8:9], 0, v[14:15]
	s_waitcnt lgkmcnt(0)
	v_cvt_pk_bf16_f32 v4, v4, v5
	ds_read2_b32 v[6:7], v12 offset0:142 offset1:207
	s_waitcnt lgkmcnt(0)
	v_cvt_pk_bf16_f32 v5, v6, v7
	global_store_dwordx4 v[10:11], v[2:5], off
	v_or_b32_e32 v10, s0, v83
	v_mul_u32_u24_e32 v10, 0x1600, v10
	ds_read2_b32 v[6:7], v81 offset0:16 offset1:81
	s_waitcnt lgkmcnt(0)
	v_cvt_pk_bf16_f32 v2, v6, v7
	ds_read2_b32 v[4:5], v81 offset0:146 offset1:211
	v_lshlrev_b32_e32 v14, 1, v10
	s_waitcnt lgkmcnt(0)
	v_cvt_pk_bf16_f32 v3, v4, v5
	ds_read2_b32 v[4:5], v12 offset0:20 offset1:85
	v_lshl_add_u64 v[10:11], v[8:9], 0, v[14:15]
	s_waitcnt lgkmcnt(0)
	v_cvt_pk_bf16_f32 v4, v4, v5
	ds_read2_b32 v[6:7], v12 offset0:150 offset1:215
	s_waitcnt lgkmcnt(0)
	v_cvt_pk_bf16_f32 v5, v6, v7
	global_store_dwordx4 v[10:11], v[2:5], off
	v_or_b32_e32 v10, s0, v84
	v_mul_u32_u24_e32 v10, 0x1600, v10
	ds_read2_b32 v[6:7], v81 offset0:24 offset1:89
	s_waitcnt lgkmcnt(0)
	v_cvt_pk_bf16_f32 v2, v6, v7
	ds_read2_b32 v[4:5], v81 offset0:154 offset1:219
	v_lshlrev_b32_e32 v14, 1, v10
	s_waitcnt lgkmcnt(0)
	v_cvt_pk_bf16_f32 v3, v4, v5
	ds_read2_b32 v[4:5], v12 offset0:28 offset1:93
	v_lshl_add_u64 v[10:11], v[8:9], 0, v[14:15]
	s_waitcnt lgkmcnt(0)
	v_cvt_pk_bf16_f32 v4, v4, v5
	ds_read2_b32 v[6:7], v12 offset0:158 offset1:223
	s_waitcnt lgkmcnt(0)
	v_cvt_pk_bf16_f32 v5, v6, v7
	global_store_dwordx4 v[10:11], v[2:5], off
	v_or_b32_e32 v10, s0, v85
	v_mul_u32_u24_e32 v10, 0x1600, v10
	ds_read2_b32 v[6:7], v81 offset0:32 offset1:97
	s_waitcnt lgkmcnt(0)
	v_cvt_pk_bf16_f32 v2, v6, v7
	ds_read2_b32 v[4:5], v81 offset0:162 offset1:227
	v_lshlrev_b32_e32 v14, 1, v10
	s_waitcnt lgkmcnt(0)
	v_cvt_pk_bf16_f32 v3, v4, v5
	ds_read2_b32 v[4:5], v12 offset0:36 offset1:101
	v_lshl_add_u64 v[10:11], v[8:9], 0, v[14:15]
	s_waitcnt lgkmcnt(0)
	v_cvt_pk_bf16_f32 v4, v4, v5
	ds_read2_b32 v[6:7], v12 offset0:166 offset1:231
	s_waitcnt lgkmcnt(0)
	v_cvt_pk_bf16_f32 v5, v6, v7
	global_store_dwordx4 v[10:11], v[2:5], off
	v_or_b32_e32 v10, s0, v86
	v_mul_u32_u24_e32 v10, 0x1600, v10
	ds_read2_b32 v[6:7], v81 offset0:40 offset1:105
	s_waitcnt lgkmcnt(0)
	v_cvt_pk_bf16_f32 v2, v6, v7
	ds_read2_b32 v[4:5], v81 offset0:170 offset1:235
	v_lshlrev_b32_e32 v14, 1, v10
	s_waitcnt lgkmcnt(0)
	v_cvt_pk_bf16_f32 v3, v4, v5
	ds_read2_b32 v[4:5], v12 offset0:44 offset1:109
	v_lshl_add_u64 v[10:11], v[8:9], 0, v[14:15]
	s_waitcnt lgkmcnt(0)
	v_cvt_pk_bf16_f32 v4, v4, v5
	ds_read2_b32 v[6:7], v12 offset0:174 offset1:239
	s_waitcnt lgkmcnt(0)
	v_cvt_pk_bf16_f32 v5, v6, v7
	global_store_dwordx4 v[10:11], v[2:5], off
	v_or_b32_e32 v10, s0, v87
	ds_read2_b32 v[6:7], v81 offset0:48 offset1:113
	s_waitcnt lgkmcnt(0)
	v_cvt_pk_bf16_f32 v2, v6, v7
	ds_read2_b32 v[4:5], v81 offset0:178 offset1:243
	v_mul_u32_u24_e32 v10, 0x1600, v10
	s_waitcnt lgkmcnt(0)
	v_cvt_pk_bf16_f32 v3, v4, v5
	ds_read2_b32 v[4:5], v12 offset0:52 offset1:117
	v_lshlrev_b32_e32 v14, 1, v10
	s_waitcnt lgkmcnt(0)
	v_cvt_pk_bf16_f32 v4, v4, v5
	ds_read2_b32 v[6:7], v12 offset0:182 offset1:247
	s_waitcnt lgkmcnt(0)
	v_cvt_pk_bf16_f32 v5, v6, v7
	v_lshl_add_u64 v[10:11], v[8:9], 0, v[14:15]
	ds_read2_b32 v[6:7], v81 offset0:56 offset1:121
	global_store_dwordx4 v[10:11], v[2:5], off
	s_waitcnt lgkmcnt(0)
	s_nop 0
	v_cvt_pk_bf16_f32 v2, v6, v7
	ds_read2_b32 v[4:5], v81 offset0:186 offset1:251
	s_waitcnt lgkmcnt(0)
	v_cvt_pk_bf16_f32 v3, v4, v5
	ds_read2_b32 v[4:5], v12 offset0:60 offset1:125
	s_waitcnt lgkmcnt(0)
	v_cvt_pk_bf16_f32 v4, v4, v5
	v_or_b32_e32 v5, s0, v88
	v_mul_u32_u24_e32 v5, 0x1600, v5
	ds_read2_b32 v[6:7], v12 offset0:190 offset1:255
	v_lshlrev_b32_e32 v14, 1, v5
	s_waitcnt lgkmcnt(0)
	v_cvt_pk_bf16_f32 v5, v6, v7
	v_lshl_add_u64 v[6:7], v[8:9], 0, v[14:15]
	global_store_dwordx4 v[6:7], v[2:5], off
	s_waitcnt lgkmcnt(0)

.LBB0_40:
	v_lshl_add_u64 v[66:67], v[10:11], 0, s[0:1]
	v_add_co_u32_e32 v76, vcc, 0xb000, v66
	v_lshl_add_u64 v[64:65], v[12:13], 0, s[0:1]
	s_nop 0
	v_addc_co_u32_e32 v77, vcc, 0, v67, vcc
	v_add_co_u32_e32 v108, vcc, 0x16000, v66
	v_lshl_add_u64 v[68:69], v[8:9], 0, s[0:1]
	s_nop 0
	v_addc_co_u32_e32 v109, vcc, 0, v67, vcc
	v_lshl_add_u64 v[70:71], v[6:7], 0, s[0:1]
	v_lshl_add_u64 v[72:73], v[4:5], 0, s[0:1]
	v_lshl_add_u64 v[74:75], v[2:3], 0, s[0:1]
	v_add_co_u32_e32 v66, vcc, 0x21000, v66
	global_load_dwordx2 v[64:65], v[64:65], off
	s_nop 0
	global_load_dwordx2 v[68:69], v[68:69], off
	s_nop 0
	global_load_dwordx2 v[70:71], v[70:71], off
	s_nop 0
	global_load_dwordx2 v[72:73], v[72:73], off
	s_nop 0
	global_load_dwordx2 v[74:75], v[74:75], off
	v_addc_co_u32_e32 v67, vcc, 0, v67, vcc
	global_load_dwordx2 v[76:77], v[76:77], off
	s_nop 0
	global_load_dwordx2 v[108:109], v[108:109], off
	s_nop 0
	global_load_dwordx2 v[66:67], v[66:67], off
	s_add_u32 s0, s0, 0x58000
	s_addc_u32 s1, s1, 0
	v_lshl_add_u64 v[164:165], v[10:11], 0, s[0:1]
	v_add_co_u32_e32 v160, vcc, 0xb000, v164
	v_lshl_add_u64 v[150:151], v[12:13], 0, s[0:1]
	s_nop 0
	v_addc_co_u32_e32 v161, vcc, 0, v165, vcc
	v_add_co_u32_e32 v162, vcc, 0x16000, v164
	v_lshl_add_u64 v[152:153], v[8:9], 0, s[0:1]
	s_nop 0
	v_addc_co_u32_e32 v163, vcc, 0, v165, vcc
	v_lshl_add_u64 v[154:155], v[6:7], 0, s[0:1]
	v_lshl_add_u64 v[156:157], v[4:5], 0, s[0:1]
	v_lshl_add_u64 v[158:159], v[2:3], 0, s[0:1]
	v_add_co_u32_e32 v164, vcc, 0x21000, v164
	global_load_dwordx2 v[150:151], v[150:151], off
	s_nop 0
	global_load_dwordx2 v[152:153], v[152:153], off
	s_nop 0
	global_load_dwordx2 v[154:155], v[154:155], off
	s_nop 0
	global_load_dwordx2 v[156:157], v[156:157], off
	s_nop 0
	global_load_dwordx2 v[158:159], v[158:159], off
	v_addc_co_u32_e32 v165, vcc, 0, v165, vcc
	global_load_dwordx2 v[160:161], v[160:161], off
	s_nop 0
	global_load_dwordx2 v[162:163], v[162:163], off
	s_nop 0
	global_load_dwordx2 v[164:165], v[164:165], off
	s_add_u32 s0, s0, 0x58000
	s_addc_u32 s1, s1, 0
	v_lshl_add_u64 v[180:181], v[10:11], 0, s[0:1]
	v_add_co_u32_e32 v176, vcc, 0xb000, v180
	v_lshl_add_u64 v[166:167], v[12:13], 0, s[0:1]
	s_nop 0
	v_addc_co_u32_e32 v177, vcc, 0, v181, vcc
	v_add_co_u32_e32 v178, vcc, 0x16000, v180
	v_lshl_add_u64 v[168:169], v[8:9], 0, s[0:1]
	s_nop 0
	v_addc_co_u32_e32 v179, vcc, 0, v181, vcc
	v_lshl_add_u64 v[170:171], v[6:7], 0, s[0:1]
	v_lshl_add_u64 v[172:173], v[4:5], 0, s[0:1]
	v_lshl_add_u64 v[174:175], v[2:3], 0, s[0:1]
	v_add_co_u32_e32 v180, vcc, 0x21000, v180
	global_load_dwordx2 v[166:167], v[166:167], off
	s_nop 0
	global_load_dwordx2 v[168:169], v[168:169], off
	s_nop 0
	global_load_dwordx2 v[170:171], v[170:171], off
	s_nop 0
	global_load_dwordx2 v[172:173], v[172:173], off
	s_nop 0
	global_load_dwordx2 v[174:175], v[174:175], off
	v_addc_co_u32_e32 v181, vcc, 0, v181, vcc
	global_load_dwordx2 v[176:177], v[176:177], off
	s_nop 0
	global_load_dwordx2 v[178:179], v[178:179], off
	s_nop 0
	global_load_dwordx2 v[180:181], v[180:181], off
	s_add_u32 s0, s0, 0x58000
	s_addc_u32 s1, s1, 0
	v_lshl_add_u64 v[196:197], v[10:11], 0, s[0:1]
	v_add_co_u32_e32 v192, vcc, 0xb000, v196
	v_lshl_add_u64 v[182:183], v[12:13], 0, s[0:1]
	s_nop 0
	v_addc_co_u32_e32 v193, vcc, 0, v197, vcc
	v_add_co_u32_e32 v194, vcc, 0x16000, v196
	v_lshl_add_u64 v[184:185], v[8:9], 0, s[0:1]
	s_nop 0
	v_addc_co_u32_e32 v195, vcc, 0, v197, vcc
	v_lshl_add_u64 v[186:187], v[6:7], 0, s[0:1]
	v_lshl_add_u64 v[188:189], v[4:5], 0, s[0:1]
	v_lshl_add_u64 v[190:191], v[2:3], 0, s[0:1]
	v_add_co_u32_e32 v196, vcc, 0x21000, v196
	global_load_dwordx2 v[182:183], v[182:183], off
	s_nop 0
	global_load_dwordx2 v[184:185], v[184:185], off
	s_nop 0
	global_load_dwordx2 v[186:187], v[186:187], off
	s_nop 0
	global_load_dwordx2 v[188:189], v[188:189], off
	s_nop 0
	global_load_dwordx2 v[190:191], v[190:191], off
	v_addc_co_u32_e32 v197, vcc, 0, v197, vcc
	global_load_dwordx2 v[192:193], v[192:193], off
	s_nop 0
	global_load_dwordx2 v[194:195], v[194:195], off
	s_nop 0
	global_load_dwordx2 v[196:197], v[196:197], off
	s_add_u32 s0, s0, 0x58000
	s_addc_u32 s1, s1, 0
	v_add_u32_e32 v63, 0x410, v14
	v_add_u32_e32 v110, 0x618, v14
	v_add_u32_e32 v111, 0x820, v14
	v_add_u32_e32 v112, 0xa28, v14
	v_add_u32_e32 v113, 0xc30, v14
	v_add_u32_e32 v114, 0xe38, v14
	s_waitcnt vmcnt(31)
	ds_write2_b32 v14, v64, v65 offset1:1
	s_waitcnt vmcnt(30)
	ds_write2_b32 v111, v68, v69 offset1:1
	s_waitcnt vmcnt(29)
	ds_write2_b32 v112, v70, v71 offset1:1
	s_waitcnt vmcnt(28)
	ds_write2_b32 v113, v72, v73 offset1:1
	s_waitcnt vmcnt(27)
	ds_write2_b32 v114, v74, v75 offset1:1
	s_waitcnt vmcnt(26)
	ds_write2_b32 v14, v76, v77 offset0:130 offset1:131
	v_add_u32_e32 v14, 0x1040, v14
	s_waitcnt vmcnt(25)
	ds_write2_b32 v63, v108, v109 offset1:1
	s_waitcnt vmcnt(24)
	ds_write2_b32 v110, v66, v67 offset1:1
	v_add_u32_e32 v63, 0x410, v14
	v_add_u32_e32 v110, 0x618, v14
	v_add_u32_e32 v111, 0x820, v14
	v_add_u32_e32 v112, 0xa28, v14
	v_add_u32_e32 v113, 0xc30, v14
	v_add_u32_e32 v114, 0xe38, v14
	s_waitcnt vmcnt(23)
	ds_write2_b32 v14, v150, v151 offset1:1
	s_waitcnt vmcnt(22)
	ds_write2_b32 v111, v152, v153 offset1:1
	s_waitcnt vmcnt(21)
	ds_write2_b32 v112, v154, v155 offset1:1
	s_waitcnt vmcnt(20)
	ds_write2_b32 v113, v156, v157 offset1:1
	s_waitcnt vmcnt(19)
	ds_write2_b32 v114, v158, v159 offset1:1
	s_waitcnt vmcnt(18)
	ds_write2_b32 v14, v160, v161 offset0:130 offset1:131
	v_add_u32_e32 v14, 0x1040, v14
	s_waitcnt vmcnt(17)
	ds_write2_b32 v63, v162, v163 offset1:1
	s_waitcnt vmcnt(16)
	ds_write2_b32 v110, v164, v165 offset1:1
	v_add_u32_e32 v63, 0x410, v14
	v_add_u32_e32 v110, 0x618, v14
	v_add_u32_e32 v111, 0x820, v14
	v_add_u32_e32 v112, 0xa28, v14
	v_add_u32_e32 v113, 0xc30, v14
	v_add_u32_e32 v114, 0xe38, v14
	s_waitcnt vmcnt(15)
	ds_write2_b32 v14, v166, v167 offset1:1
	s_waitcnt vmcnt(14)
	ds_write2_b32 v111, v168, v169 offset1:1
	s_waitcnt vmcnt(13)
	ds_write2_b32 v112, v170, v171 offset1:1
	s_waitcnt vmcnt(12)
	ds_write2_b32 v113, v172, v173 offset1:1
	s_waitcnt vmcnt(11)
	ds_write2_b32 v114, v174, v175 offset1:1
	s_waitcnt vmcnt(10)
	ds_write2_b32 v14, v176, v177 offset0:130 offset1:131
	v_add_u32_e32 v14, 0x1040, v14
	s_waitcnt vmcnt(9)
	ds_write2_b32 v63, v178, v179 offset1:1
	s_waitcnt vmcnt(8)
	ds_write2_b32 v110, v180, v181 offset1:1
	v_add_u32_e32 v63, 0x410, v14
	v_add_u32_e32 v110, 0x618, v14
	v_add_u32_e32 v111, 0x820, v14
	v_add_u32_e32 v112, 0xa28, v14
	v_add_u32_e32 v113, 0xc30, v14
	v_add_u32_e32 v114, 0xe38, v14
	s_waitcnt vmcnt(7)
	ds_write2_b32 v14, v182, v183 offset1:1
	s_waitcnt vmcnt(6)
	ds_write2_b32 v111, v184, v185 offset1:1
	s_waitcnt vmcnt(5)
	ds_write2_b32 v112, v186, v187 offset1:1
	s_waitcnt vmcnt(4)
	ds_write2_b32 v113, v188, v189 offset1:1
	s_waitcnt vmcnt(3)
	ds_write2_b32 v114, v190, v191 offset1:1
	s_waitcnt vmcnt(2)
	ds_write2_b32 v14, v192, v193 offset0:130 offset1:131
	v_add_u32_e32 v14, 0x1040, v14
	s_waitcnt vmcnt(1)
	ds_write2_b32 v63, v194, v195 offset1:1
	s_waitcnt vmcnt(0)
	ds_write2_b32 v110, v196, v197 offset1:1
	s_lshl_b32 s0, s2, 7
	s_and_b32 s1, s3, 64
	s_waitcnt lgkmcnt(0)
	s_or_b32 s0, s1, s0
	ds_read2_b32 v[2:3], v81 offset1:65
	s_and_b32 s2, 0xffff, s4
	s_bitset1_b32 s0, 7
	s_waitcnt lgkmcnt(0)
	v_cvt_pk_bf16_f32 v2, v2, v3
	ds_read2_b32 v[4:5], v81 offset0:130 offset1:195
	v_add_u32_e32 v12, 0x400, v81
	s_lshl_b32 s8, s2, 1
	v_or_b32_e32 v10, s0, v80
	s_waitcnt lgkmcnt(0)
	v_cvt_pk_bf16_f32 v3, v4, v5
	ds_read2_b32 v[4:5], v12 offset0:4 offset1:69
	v_lshl_add_u64 v[8:9], v[24:25], 0, s[8:9]
	v_lshlrev_b32_e32 v14, 12, v10
	s_waitcnt lgkmcnt(0)
	v_cvt_pk_bf16_f32 v4, v4, v5
	ds_read2_b32 v[6:7], v12 offset0:134 offset1:199
	s_waitcnt lgkmcnt(0)
	v_cvt_pk_bf16_f32 v5, v6, v7
	v_lshl_add_u64 v[10:11], v[8:9], 0, v[14:15]
	ds_read2_b32 v[6:7], v81 offset0:8 offset1:73
	global_store_dwordx4 v[10:11], v[2:5], off
	v_or_b32_e32 v10, s0, v82
	v_lshlrev_b32_e32 v14, 12, v10
	s_waitcnt lgkmcnt(0)
	v_cvt_pk_bf16_f32 v2, v6, v7
	ds_read2_b32 v[4:5], v81 offset0:138 offset1:203
	s_waitcnt lgkmcnt(0)
	v_cvt_pk_bf16_f32 v3, v4, v5
	ds_read2_b32 v[4:5], v12 offset0:12 offset1:77
	s_waitcnt lgkmcnt(0)
	v_cvt_pk_bf16_f32 v4, v4, v5
	ds_read2_b32 v[6:7], v12 offset0:142 offset1:207
	s_waitcnt lgkmcnt(0)
	v_cvt_pk_bf16_f32 v5, v6, v7
	v_lshl_add_u64 v[10:11], v[8:9], 0, v[14:15]
	ds_read2_b32 v[6:7], v81 offset0:16 offset1:81
	global_store_dwordx4 v[10:11], v[2:5], off
	v_or_b32_e32 v10, s0, v83
	v_lshlrev_b32_e32 v14, 12, v10
	s_waitcnt lgkmcnt(0)
	v_cvt_pk_bf16_f32 v2, v6, v7
	ds_read2_b32 v[4:5], v81 offset0:146 offset1:211
	s_waitcnt lgkmcnt(0)
	v_cvt_pk_bf16_f32 v3, v4, v5
	ds_read2_b32 v[4:5], v12 offset0:20 offset1:85
	s_waitcnt lgkmcnt(0)
	v_cvt_pk_bf16_f32 v4, v4, v5
	ds_read2_b32 v[6:7], v12 offset0:150 offset1:215
	s_waitcnt lgkmcnt(0)
	v_cvt_pk_bf16_f32 v5, v6, v7
	v_lshl_add_u64 v[10:11], v[8:9], 0, v[14:15]
	ds_read2_b32 v[6:7], v81 offset0:24 offset1:89
	global_store_dwordx4 v[10:11], v[2:5], off
	v_or_b32_e32 v10, s0, v84
	v_lshlrev_b32_e32 v14, 12, v10
	s_waitcnt lgkmcnt(0)
	v_cvt_pk_bf16_f32 v2, v6, v7
	ds_read2_b32 v[4:5], v81 offset0:154 offset1:219
	s_waitcnt lgkmcnt(0)
	v_cvt_pk_bf16_f32 v3, v4, v5
	ds_read2_b32 v[4:5], v12 offset0:28 offset1:93
	s_waitcnt lgkmcnt(0)
	v_cvt_pk_bf16_f32 v4, v4, v5
	ds_read2_b32 v[6:7], v12 offset0:158 offset1:223
	s_waitcnt lgkmcnt(0)
	v_cvt_pk_bf16_f32 v5, v6, v7
	v_lshl_add_u64 v[10:11], v[8:9], 0, v[14:15]
	ds_read2_b32 v[6:7], v81 offset0:32 offset1:97
	global_store_dwordx4 v[10:11], v[2:5], off
	v_or_b32_e32 v10, s0, v85
	v_lshlrev_b32_e32 v14, 12, v10
	s_waitcnt lgkmcnt(0)
	v_cvt_pk_bf16_f32 v2, v6, v7
	ds_read2_b32 v[4:5], v81 offset0:162 offset1:227
	s_waitcnt lgkmcnt(0)
	v_cvt_pk_bf16_f32 v3, v4, v5
	ds_read2_b32 v[4:5], v12 offset0:36 offset1:101
	s_waitcnt lgkmcnt(0)
	v_cvt_pk_bf16_f32 v4, v4, v5
	ds_read2_b32 v[6:7], v12 offset0:166 offset1:231
	s_waitcnt lgkmcnt(0)
	v_cvt_pk_bf16_f32 v5, v6, v7
	v_lshl_add_u64 v[10:11], v[8:9], 0, v[14:15]
	ds_read2_b32 v[6:7], v81 offset0:40 offset1:105
	global_store_dwordx4 v[10:11], v[2:5], off
	v_or_b32_e32 v10, s0, v86
	v_lshlrev_b32_e32 v14, 12, v10
	s_waitcnt lgkmcnt(0)
	v_cvt_pk_bf16_f32 v2, v6, v7
	ds_read2_b32 v[4:5], v81 offset0:170 offset1:235
	s_waitcnt lgkmcnt(0)
	v_cvt_pk_bf16_f32 v3, v4, v5
	ds_read2_b32 v[4:5], v12 offset0:44 offset1:109
	s_waitcnt lgkmcnt(0)
	v_cvt_pk_bf16_f32 v4, v4, v5
	ds_read2_b32 v[6:7], v12 offset0:174 offset1:239
	s_waitcnt lgkmcnt(0)
	v_cvt_pk_bf16_f32 v5, v6, v7
	v_lshl_add_u64 v[10:11], v[8:9], 0, v[14:15]
	ds_read2_b32 v[6:7], v81 offset0:48 offset1:113
	global_store_dwordx4 v[10:11], v[2:5], off
	v_or_b32_e32 v10, s0, v87
	v_lshlrev_b32_e32 v14, 12, v10
	s_waitcnt lgkmcnt(0)
	v_cvt_pk_bf16_f32 v2, v6, v7
	ds_read2_b32 v[4:5], v81 offset0:178 offset1:243
	s_waitcnt lgkmcnt(0)
	v_cvt_pk_bf16_f32 v3, v4, v5
	ds_read2_b32 v[4:5], v12 offset0:52 offset1:117
	s_waitcnt lgkmcnt(0)
	v_cvt_pk_bf16_f32 v4, v4, v5
	ds_read2_b32 v[6:7], v12 offset0:182 offset1:247
	s_waitcnt lgkmcnt(0)
	v_cvt_pk_bf16_f32 v5, v6, v7
	v_lshl_add_u64 v[10:11], v[8:9], 0, v[14:15]
	ds_read2_b32 v[6:7], v81 offset0:56 offset1:121
	global_store_dwordx4 v[10:11], v[2:5], off
	s_waitcnt lgkmcnt(0)
	s_nop 0
	v_cvt_pk_bf16_f32 v2, v6, v7
	ds_read2_b32 v[4:5], v81 offset0:186 offset1:251
	s_waitcnt lgkmcnt(0)
	v_cvt_pk_bf16_f32 v3, v4, v5
	ds_read2_b32 v[4:5], v12 offset0:60 offset1:125
	s_waitcnt lgkmcnt(0)
	v_cvt_pk_bf16_f32 v4, v4, v5
	v_or_b32_e32 v5, s0, v88
	ds_read2_b32 v[6:7], v12 offset0:190 offset1:255
	v_lshlrev_b32_e32 v14, 12, v5
	s_waitcnt lgkmcnt(0)
	v_cvt_pk_bf16_f32 v5, v6, v7
	v_lshl_add_u64 v[6:7], v[8:9], 0, v[14:15]
	global_store_dwordx4 v[6:7], v[2:5], off
	s_waitcnt lgkmcnt(0)

.LBB0_45:
	v_lshl_add_u64 v[66:67], v[10:11], 0, s[0:1]
	v_add_co_u32_e32 v76, vcc, 0xb000, v66
	v_lshl_add_u64 v[64:65], v[12:13], 0, s[0:1]
	s_nop 0
	v_addc_co_u32_e32 v77, vcc, 0, v67, vcc
	v_add_co_u32_e32 v108, vcc, 0x16000, v66
	v_lshl_add_u64 v[68:69], v[8:9], 0, s[0:1]
	s_nop 0
	v_addc_co_u32_e32 v109, vcc, 0, v67, vcc
	v_lshl_add_u64 v[70:71], v[6:7], 0, s[0:1]
	v_lshl_add_u64 v[72:73], v[4:5], 0, s[0:1]
	v_lshl_add_u64 v[74:75], v[2:3], 0, s[0:1]
	v_add_co_u32_e32 v66, vcc, 0x21000, v66
	global_load_dwordx2 v[64:65], v[64:65], off
	s_nop 0
	global_load_dwordx2 v[68:69], v[68:69], off
	s_nop 0
	global_load_dwordx2 v[70:71], v[70:71], off
	s_nop 0
	global_load_dwordx2 v[72:73], v[72:73], off
	s_nop 0
	global_load_dwordx2 v[74:75], v[74:75], off
	v_addc_co_u32_e32 v67, vcc, 0, v67, vcc
	global_load_dwordx2 v[76:77], v[76:77], off
	s_nop 0
	global_load_dwordx2 v[108:109], v[108:109], off
	s_nop 0
	global_load_dwordx2 v[66:67], v[66:67], off
	s_add_u32 s0, s0, 0x58000
	s_addc_u32 s1, s1, 0
	v_lshl_add_u64 v[164:165], v[10:11], 0, s[0:1]
	v_add_co_u32_e32 v160, vcc, 0xb000, v164
	v_lshl_add_u64 v[150:151], v[12:13], 0, s[0:1]
	s_nop 0
	v_addc_co_u32_e32 v161, vcc, 0, v165, vcc
	v_add_co_u32_e32 v162, vcc, 0x16000, v164
	v_lshl_add_u64 v[152:153], v[8:9], 0, s[0:1]
	s_nop 0
	v_addc_co_u32_e32 v163, vcc, 0, v165, vcc
	v_lshl_add_u64 v[154:155], v[6:7], 0, s[0:1]
	v_lshl_add_u64 v[156:157], v[4:5], 0, s[0:1]
	v_lshl_add_u64 v[158:159], v[2:3], 0, s[0:1]
	v_add_co_u32_e32 v164, vcc, 0x21000, v164
	global_load_dwordx2 v[150:151], v[150:151], off
	s_nop 0
	global_load_dwordx2 v[152:153], v[152:153], off
	s_nop 0
	global_load_dwordx2 v[154:155], v[154:155], off
	s_nop 0
	global_load_dwordx2 v[156:157], v[156:157], off
	s_nop 0
	global_load_dwordx2 v[158:159], v[158:159], off
	v_addc_co_u32_e32 v165, vcc, 0, v165, vcc
	global_load_dwordx2 v[160:161], v[160:161], off
	s_nop 0
	global_load_dwordx2 v[162:163], v[162:163], off
	s_nop 0
	global_load_dwordx2 v[164:165], v[164:165], off
	s_add_u32 s0, s0, 0x58000
	s_addc_u32 s1, s1, 0
	v_lshl_add_u64 v[180:181], v[10:11], 0, s[0:1]
	v_add_co_u32_e32 v176, vcc, 0xb000, v180
	v_lshl_add_u64 v[166:167], v[12:13], 0, s[0:1]
	s_nop 0
	v_addc_co_u32_e32 v177, vcc, 0, v181, vcc
	v_add_co_u32_e32 v178, vcc, 0x16000, v180
	v_lshl_add_u64 v[168:169], v[8:9], 0, s[0:1]
	s_nop 0
	v_addc_co_u32_e32 v179, vcc, 0, v181, vcc
	v_lshl_add_u64 v[170:171], v[6:7], 0, s[0:1]
	v_lshl_add_u64 v[172:173], v[4:5], 0, s[0:1]
	v_lshl_add_u64 v[174:175], v[2:3], 0, s[0:1]
	v_add_co_u32_e32 v180, vcc, 0x21000, v180
	global_load_dwordx2 v[166:167], v[166:167], off
	s_nop 0
	global_load_dwordx2 v[168:169], v[168:169], off
	s_nop 0
	global_load_dwordx2 v[170:171], v[170:171], off
	s_nop 0
	global_load_dwordx2 v[172:173], v[172:173], off
	s_nop 0
	global_load_dwordx2 v[174:175], v[174:175], off
	v_addc_co_u32_e32 v181, vcc, 0, v181, vcc
	global_load_dwordx2 v[176:177], v[176:177], off
	s_nop 0
	global_load_dwordx2 v[178:179], v[178:179], off
	s_nop 0
	global_load_dwordx2 v[180:181], v[180:181], off
	s_add_u32 s0, s0, 0x58000
	s_addc_u32 s1, s1, 0
	v_lshl_add_u64 v[196:197], v[10:11], 0, s[0:1]
	v_add_co_u32_e32 v192, vcc, 0xb000, v196
	v_lshl_add_u64 v[182:183], v[12:13], 0, s[0:1]
	s_nop 0
	v_addc_co_u32_e32 v193, vcc, 0, v197, vcc
	v_add_co_u32_e32 v194, vcc, 0x16000, v196
	v_lshl_add_u64 v[184:185], v[8:9], 0, s[0:1]
	s_nop 0
	v_addc_co_u32_e32 v195, vcc, 0, v197, vcc
	v_lshl_add_u64 v[186:187], v[6:7], 0, s[0:1]
	v_lshl_add_u64 v[188:189], v[4:5], 0, s[0:1]
	v_lshl_add_u64 v[190:191], v[2:3], 0, s[0:1]
	v_add_co_u32_e32 v196, vcc, 0x21000, v196
	global_load_dwordx2 v[182:183], v[182:183], off
	s_nop 0
	global_load_dwordx2 v[184:185], v[184:185], off
	s_nop 0
	global_load_dwordx2 v[186:187], v[186:187], off
	s_nop 0
	global_load_dwordx2 v[188:189], v[188:189], off
	s_nop 0
	global_load_dwordx2 v[190:191], v[190:191], off
	v_addc_co_u32_e32 v197, vcc, 0, v197, vcc
	global_load_dwordx2 v[192:193], v[192:193], off
	s_nop 0
	global_load_dwordx2 v[194:195], v[194:195], off
	s_nop 0
	global_load_dwordx2 v[196:197], v[196:197], off
	s_add_u32 s0, s0, 0x58000
	s_addc_u32 s1, s1, 0
	v_add_u32_e32 v63, 0x410, v14
	v_add_u32_e32 v110, 0x618, v14
	v_add_u32_e32 v111, 0x820, v14
	v_add_u32_e32 v112, 0xa28, v14
	v_add_u32_e32 v113, 0xc30, v14
	v_add_u32_e32 v114, 0xe38, v14
	s_waitcnt vmcnt(31)
	ds_write2_b32 v14, v64, v65 offset1:1
	s_waitcnt vmcnt(30)
	ds_write2_b32 v111, v68, v69 offset1:1
	s_waitcnt vmcnt(29)
	ds_write2_b32 v112, v70, v71 offset1:1
	s_waitcnt vmcnt(28)
	ds_write2_b32 v113, v72, v73 offset1:1
	s_waitcnt vmcnt(27)
	ds_write2_b32 v114, v74, v75 offset1:1
	s_waitcnt vmcnt(26)
	ds_write2_b32 v14, v76, v77 offset0:130 offset1:131
	v_add_u32_e32 v14, 0x1040, v14
	s_waitcnt vmcnt(25)
	ds_write2_b32 v63, v108, v109 offset1:1
	s_waitcnt vmcnt(24)
	ds_write2_b32 v110, v66, v67 offset1:1
	v_add_u32_e32 v63, 0x410, v14
	v_add_u32_e32 v110, 0x618, v14
	v_add_u32_e32 v111, 0x820, v14
	v_add_u32_e32 v112, 0xa28, v14
	v_add_u32_e32 v113, 0xc30, v14
	v_add_u32_e32 v114, 0xe38, v14
	s_waitcnt vmcnt(23)
	ds_write2_b32 v14, v150, v151 offset1:1
	s_waitcnt vmcnt(22)
	ds_write2_b32 v111, v152, v153 offset1:1
	s_waitcnt vmcnt(21)
	ds_write2_b32 v112, v154, v155 offset1:1
	s_waitcnt vmcnt(20)
	ds_write2_b32 v113, v156, v157 offset1:1
	s_waitcnt vmcnt(19)
	ds_write2_b32 v114, v158, v159 offset1:1
	s_waitcnt vmcnt(18)
	ds_write2_b32 v14, v160, v161 offset0:130 offset1:131
	v_add_u32_e32 v14, 0x1040, v14
	s_waitcnt vmcnt(17)
	ds_write2_b32 v63, v162, v163 offset1:1
	s_waitcnt vmcnt(16)
	ds_write2_b32 v110, v164, v165 offset1:1
	v_add_u32_e32 v63, 0x410, v14
	v_add_u32_e32 v110, 0x618, v14
	v_add_u32_e32 v111, 0x820, v14
	v_add_u32_e32 v112, 0xa28, v14
	v_add_u32_e32 v113, 0xc30, v14
	v_add_u32_e32 v114, 0xe38, v14
	s_waitcnt vmcnt(15)
	ds_write2_b32 v14, v166, v167 offset1:1
	s_waitcnt vmcnt(14)
	ds_write2_b32 v111, v168, v169 offset1:1
	s_waitcnt vmcnt(13)
	ds_write2_b32 v112, v170, v171 offset1:1
	s_waitcnt vmcnt(12)
	ds_write2_b32 v113, v172, v173 offset1:1
	s_waitcnt vmcnt(11)
	ds_write2_b32 v114, v174, v175 offset1:1
	s_waitcnt vmcnt(10)
	ds_write2_b32 v14, v176, v177 offset0:130 offset1:131
	v_add_u32_e32 v14, 0x1040, v14
	s_waitcnt vmcnt(9)
	ds_write2_b32 v63, v178, v179 offset1:1
	s_waitcnt vmcnt(8)
	ds_write2_b32 v110, v180, v181 offset1:1
	v_add_u32_e32 v63, 0x410, v14
	v_add_u32_e32 v110, 0x618, v14
	v_add_u32_e32 v111, 0x820, v14
	v_add_u32_e32 v112, 0xa28, v14
	v_add_u32_e32 v113, 0xc30, v14
	v_add_u32_e32 v114, 0xe38, v14
	s_waitcnt vmcnt(7)
	ds_write2_b32 v14, v182, v183 offset1:1
	s_waitcnt vmcnt(6)
	ds_write2_b32 v111, v184, v185 offset1:1
	s_waitcnt vmcnt(5)
	ds_write2_b32 v112, v186, v187 offset1:1
	s_waitcnt vmcnt(4)
	ds_write2_b32 v113, v188, v189 offset1:1
	s_waitcnt vmcnt(3)
	ds_write2_b32 v114, v190, v191 offset1:1
	s_waitcnt vmcnt(2)
	ds_write2_b32 v14, v192, v193 offset0:130 offset1:131
	v_add_u32_e32 v14, 0x1040, v14
	s_waitcnt vmcnt(1)
	ds_write2_b32 v63, v194, v195 offset1:1
	s_waitcnt vmcnt(0)
	ds_write2_b32 v110, v196, v197 offset1:1
	s_lshl_b32 s0, s2, 7
	s_waitcnt lgkmcnt(0)
	s_and_b32 s1, s3, 64
	s_and_b32 s0, s0, 0x3f00
	ds_read2_b32 v[2:3], v81 offset1:65
	s_and_b32 s2, 0xffff, s4
	s_or_b32 s0, s0, s1
	s_waitcnt lgkmcnt(0)
	v_cvt_pk_bf16_f32 v2, v2, v3
	ds_read2_b32 v[4:5], v81 offset0:130 offset1:195
	v_add_u32_e32 v12, 0x400, v81
	s_lshl_b32 s8, s2, 1
	v_or_b32_e32 v10, s0, v80
	s_waitcnt lgkmcnt(0)
	v_cvt_pk_bf16_f32 v3, v4, v5
	ds_read2_b32 v[4:5], v12 offset0:4 offset1:69
	v_lshl_add_u64 v[8:9], v[24:25], 0, s[8:9]
	v_lshlrev_b32_e32 v14, 12, v10
	s_waitcnt lgkmcnt(0)
	v_cvt_pk_bf16_f32 v4, v4, v5
	ds_read2_b32 v[6:7], v12 offset0:134 offset1:199
	s_waitcnt lgkmcnt(0)
	v_cvt_pk_bf16_f32 v5, v6, v7
	v_lshl_add_u64 v[10:11], v[8:9], 0, v[14:15]
	ds_read2_b32 v[6:7], v81 offset0:8 offset1:73
	global_store_dwordx4 v[10:11], v[2:5], off
	v_or_b32_e32 v10, s0, v82
	v_lshlrev_b32_e32 v14, 12, v10
	s_waitcnt lgkmcnt(0)
	v_cvt_pk_bf16_f32 v2, v6, v7
	ds_read2_b32 v[4:5], v81 offset0:138 offset1:203
	s_waitcnt lgkmcnt(0)
	v_cvt_pk_bf16_f32 v3, v4, v5
	ds_read2_b32 v[4:5], v12 offset0:12 offset1:77
	s_waitcnt lgkmcnt(0)
	v_cvt_pk_bf16_f32 v4, v4, v5
	ds_read2_b32 v[6:7], v12 offset0:142 offset1:207
	s_waitcnt lgkmcnt(0)
	v_cvt_pk_bf16_f32 v5, v6, v7
	v_lshl_add_u64 v[10:11], v[8:9], 0, v[14:15]
	ds_read2_b32 v[6:7], v81 offset0:16 offset1:81
	global_store_dwordx4 v[10:11], v[2:5], off
	v_or_b32_e32 v10, s0, v83
	v_lshlrev_b32_e32 v14, 12, v10
	s_waitcnt lgkmcnt(0)
	v_cvt_pk_bf16_f32 v2, v6, v7
	ds_read2_b32 v[4:5], v81 offset0:146 offset1:211
	s_waitcnt lgkmcnt(0)
	v_cvt_pk_bf16_f32 v3, v4, v5
	ds_read2_b32 v[4:5], v12 offset0:20 offset1:85
	s_waitcnt lgkmcnt(0)
	v_cvt_pk_bf16_f32 v4, v4, v5
	ds_read2_b32 v[6:7], v12 offset0:150 offset1:215
	s_waitcnt lgkmcnt(0)
	v_cvt_pk_bf16_f32 v5, v6, v7
	v_lshl_add_u64 v[10:11], v[8:9], 0, v[14:15]
	ds_read2_b32 v[6:7], v81 offset0:24 offset1:89
	global_store_dwordx4 v[10:11], v[2:5], off
	v_or_b32_e32 v10, s0, v84
	v_lshlrev_b32_e32 v14, 12, v10
	s_waitcnt lgkmcnt(0)
	v_cvt_pk_bf16_f32 v2, v6, v7
	ds_read2_b32 v[4:5], v81 offset0:154 offset1:219
	s_waitcnt lgkmcnt(0)
	v_cvt_pk_bf16_f32 v3, v4, v5
	ds_read2_b32 v[4:5], v12 offset0:28 offset1:93
	s_waitcnt lgkmcnt(0)
	v_cvt_pk_bf16_f32 v4, v4, v5
	ds_read2_b32 v[6:7], v12 offset0:158 offset1:223
	s_waitcnt lgkmcnt(0)
	v_cvt_pk_bf16_f32 v5, v6, v7
	v_lshl_add_u64 v[10:11], v[8:9], 0, v[14:15]
	ds_read2_b32 v[6:7], v81 offset0:32 offset1:97
	global_store_dwordx4 v[10:11], v[2:5], off
	v_or_b32_e32 v10, s0, v85
	v_lshlrev_b32_e32 v14, 12, v10
	s_waitcnt lgkmcnt(0)
	v_cvt_pk_bf16_f32 v2, v6, v7
	ds_read2_b32 v[4:5], v81 offset0:162 offset1:227
	s_waitcnt lgkmcnt(0)
	v_cvt_pk_bf16_f32 v3, v4, v5
	ds_read2_b32 v[4:5], v12 offset0:36 offset1:101
	s_waitcnt lgkmcnt(0)
	v_cvt_pk_bf16_f32 v4, v4, v5
	ds_read2_b32 v[6:7], v12 offset0:166 offset1:231
	s_waitcnt lgkmcnt(0)
	v_cvt_pk_bf16_f32 v5, v6, v7
	v_lshl_add_u64 v[10:11], v[8:9], 0, v[14:15]
	ds_read2_b32 v[6:7], v81 offset0:40 offset1:105
	global_store_dwordx4 v[10:11], v[2:5], off
	v_or_b32_e32 v10, s0, v86
	v_lshlrev_b32_e32 v14, 12, v10
	s_waitcnt lgkmcnt(0)
	v_cvt_pk_bf16_f32 v2, v6, v7
	ds_read2_b32 v[4:5], v81 offset0:170 offset1:235
	s_waitcnt lgkmcnt(0)
	v_cvt_pk_bf16_f32 v3, v4, v5
	ds_read2_b32 v[4:5], v12 offset0:44 offset1:109
	s_waitcnt lgkmcnt(0)
	v_cvt_pk_bf16_f32 v4, v4, v5
	ds_read2_b32 v[6:7], v12 offset0:174 offset1:239
	s_waitcnt lgkmcnt(0)
	v_cvt_pk_bf16_f32 v5, v6, v7
	v_lshl_add_u64 v[10:11], v[8:9], 0, v[14:15]
	ds_read2_b32 v[6:7], v81 offset0:48 offset1:113
	global_store_dwordx4 v[10:11], v[2:5], off
	v_or_b32_e32 v10, s0, v87
	v_lshlrev_b32_e32 v14, 12, v10
	s_waitcnt lgkmcnt(0)
	v_cvt_pk_bf16_f32 v2, v6, v7
	ds_read2_b32 v[4:5], v81 offset0:178 offset1:243
	s_waitcnt lgkmcnt(0)
	v_cvt_pk_bf16_f32 v3, v4, v5
	ds_read2_b32 v[4:5], v12 offset0:52 offset1:117
	s_waitcnt lgkmcnt(0)
	v_cvt_pk_bf16_f32 v4, v4, v5
	ds_read2_b32 v[6:7], v12 offset0:182 offset1:247
	s_waitcnt lgkmcnt(0)
	v_cvt_pk_bf16_f32 v5, v6, v7
	v_lshl_add_u64 v[10:11], v[8:9], 0, v[14:15]
	ds_read2_b32 v[6:7], v81 offset0:56 offset1:121
	global_store_dwordx4 v[10:11], v[2:5], off
	s_waitcnt lgkmcnt(0)
	s_nop 0
	v_cvt_pk_bf16_f32 v2, v6, v7
	ds_read2_b32 v[4:5], v81 offset0:186 offset1:251
	s_waitcnt lgkmcnt(0)
	v_cvt_pk_bf16_f32 v3, v4, v5
	ds_read2_b32 v[4:5], v12 offset0:60 offset1:125
	s_waitcnt lgkmcnt(0)
	v_cvt_pk_bf16_f32 v4, v4, v5
	v_or_b32_e32 v5, s0, v88
	ds_read2_b32 v[6:7], v12 offset0:190 offset1:255
	v_lshlrev_b32_e32 v14, 12, v5
	s_waitcnt lgkmcnt(0)
	v_cvt_pk_bf16_f32 v5, v6, v7
	v_lshl_add_u64 v[6:7], v[8:9], 0, v[14:15]
	global_store_dwordx4 v[6:7], v[2:5], off
	s_waitcnt lgkmcnt(0)

.LBB0_50:
	v_add_u32_e32 v5, s1, v62
	v_add_u32_e32 v14, 0xfe520000, v5
	v_lshl_add_u64 v[6:7], v[14:15], 2, v[2:3]
	v_add_u32_e32 v14, 0xfe521000, v5
	v_lshl_add_u64 v[8:9], v[14:15], 2, v[2:3]
	v_add_u32_e32 v14, 0xfe522000, v5
	v_lshl_add_u64 v[10:11], v[14:15], 2, v[2:3]
	v_add_u32_e32 v14, 0xfe523000, v5
	v_lshl_add_u64 v[12:13], v[14:15], 2, v[2:3]
	v_add_u32_e32 v14, 0xfe524000, v5
	v_lshl_add_u64 v[64:65], v[14:15], 2, v[2:3]
	v_add_u32_e32 v14, 0xfe525000, v5
	v_lshl_add_u64 v[66:67], v[14:15], 2, v[2:3]
	v_add_u32_e32 v14, 0xfe526000, v5
	v_lshl_add_u64 v[68:69], v[14:15], 2, v[2:3]
	v_add_u32_e32 v14, 0xfe527000, v5
	global_load_dwordx2 v[6:7], v[6:7], off
	s_nop 0
	global_load_dwordx2 v[8:9], v[8:9], off
	v_lshl_add_u64 v[70:71], v[14:15], 2, v[2:3]
	global_load_dwordx2 v[10:11], v[10:11], off
	s_nop 0
	global_load_dwordx2 v[12:13], v[12:13], off
	s_nop 0
	global_load_dwordx2 v[64:65], v[64:65], off
	s_nop 0
	global_load_dwordx2 v[66:67], v[66:67], off
	s_nop 0
	global_load_dwordx2 v[68:69], v[68:69], off
	s_nop 0
	global_load_dwordx2 v[70:71], v[70:71], off
	s_add_i32 s1, s1, 0x8000
	v_add_u32_e32 v5, s1, v62
	v_add_u32_e32 v14, 0xfe520000, v5
	v_lshl_add_u64 v[150:151], v[14:15], 2, v[2:3]
	v_add_u32_e32 v14, 0xfe521000, v5
	v_lshl_add_u64 v[152:153], v[14:15], 2, v[2:3]
	v_add_u32_e32 v14, 0xfe522000, v5
	v_lshl_add_u64 v[154:155], v[14:15], 2, v[2:3]
	v_add_u32_e32 v14, 0xfe523000, v5
	v_lshl_add_u64 v[156:157], v[14:15], 2, v[2:3]
	v_add_u32_e32 v14, 0xfe524000, v5
	v_lshl_add_u64 v[158:159], v[14:15], 2, v[2:3]
	v_add_u32_e32 v14, 0xfe525000, v5
	v_lshl_add_u64 v[160:161], v[14:15], 2, v[2:3]
	v_add_u32_e32 v14, 0xfe526000, v5
	v_lshl_add_u64 v[162:163], v[14:15], 2, v[2:3]
	v_add_u32_e32 v14, 0xfe527000, v5
	global_load_dwordx2 v[150:151], v[150:151], off
	s_nop 0
	global_load_dwordx2 v[152:153], v[152:153], off
	v_lshl_add_u64 v[164:165], v[14:15], 2, v[2:3]
	global_load_dwordx2 v[154:155], v[154:155], off
	s_nop 0
	global_load_dwordx2 v[156:157], v[156:157], off
	s_nop 0
	global_load_dwordx2 v[158:159], v[158:159], off
	s_nop 0
	global_load_dwordx2 v[160:161], v[160:161], off
	s_nop 0
	global_load_dwordx2 v[162:163], v[162:163], off
	s_nop 0
	global_load_dwordx2 v[164:165], v[164:165], off
	s_add_i32 s1, s1, 0x8000
	v_add_u32_e32 v5, s1, v62
	v_add_u32_e32 v14, 0xfe520000, v5
	v_lshl_add_u64 v[166:167], v[14:15], 2, v[2:3]
	v_add_u32_e32 v14, 0xfe521000, v5
	v_lshl_add_u64 v[168:169], v[14:15], 2, v[2:3]
	v_add_u32_e32 v14, 0xfe522000, v5
	v_lshl_add_u64 v[170:171], v[14:15], 2, v[2:3]
	v_add_u32_e32 v14, 0xfe523000, v5
	v_lshl_add_u64 v[172:173], v[14:15], 2, v[2:3]
	v_add_u32_e32 v14, 0xfe524000, v5
	v_lshl_add_u64 v[174:175], v[14:15], 2, v[2:3]
	v_add_u32_e32 v14, 0xfe525000, v5
	v_lshl_add_u64 v[176:177], v[14:15], 2, v[2:3]
	v_add_u32_e32 v14, 0xfe526000, v5
	v_lshl_add_u64 v[178:179], v[14:15], 2, v[2:3]
	v_add_u32_e32 v14, 0xfe527000, v5
	global_load_dwordx2 v[166:167], v[166:167], off
	s_nop 0
	global_load_dwordx2 v[168:169], v[168:169], off
	v_lshl_add_u64 v[180:181], v[14:15], 2, v[2:3]
	global_load_dwordx2 v[170:171], v[170:171], off
	s_nop 0
	global_load_dwordx2 v[172:173], v[172:173], off
	s_nop 0
	global_load_dwordx2 v[174:175], v[174:175], off
	s_nop 0
	global_load_dwordx2 v[176:177], v[176:177], off
	s_nop 0
	global_load_dwordx2 v[178:179], v[178:179], off
	s_nop 0
	global_load_dwordx2 v[180:181], v[180:181], off
	s_add_i32 s1, s1, 0x8000
	v_add_u32_e32 v5, s1, v62
	v_add_u32_e32 v14, 0xfe520000, v5
	v_lshl_add_u64 v[182:183], v[14:15], 2, v[2:3]
	v_add_u32_e32 v14, 0xfe521000, v5
	v_lshl_add_u64 v[184:185], v[14:15], 2, v[2:3]
	v_add_u32_e32 v14, 0xfe522000, v5
	v_lshl_add_u64 v[186:187], v[14:15], 2, v[2:3]
	v_add_u32_e32 v14, 0xfe523000, v5
	v_lshl_add_u64 v[188:189], v[14:15], 2, v[2:3]
	v_add_u32_e32 v14, 0xfe524000, v5
	v_lshl_add_u64 v[190:191], v[14:15], 2, v[2:3]
	v_add_u32_e32 v14, 0xfe525000, v5
	v_lshl_add_u64 v[192:193], v[14:15], 2, v[2:3]
	v_add_u32_e32 v14, 0xfe526000, v5
	v_lshl_add_u64 v[194:195], v[14:15], 2, v[2:3]
	v_add_u32_e32 v14, 0xfe527000, v5
	global_load_dwordx2 v[182:183], v[182:183], off
	s_nop 0
	global_load_dwordx2 v[184:185], v[184:185], off
	v_lshl_add_u64 v[196:197], v[14:15], 2, v[2:3]
	global_load_dwordx2 v[186:187], v[186:187], off
	s_nop 0
	global_load_dwordx2 v[188:189], v[188:189], off
	s_nop 0
	global_load_dwordx2 v[190:191], v[190:191], off
	s_nop 0
	global_load_dwordx2 v[192:193], v[192:193], off
	s_nop 0
	global_load_dwordx2 v[194:195], v[194:195], off
	s_nop 0
	global_load_dwordx2 v[196:197], v[196:197], off
	s_add_i32 s1, s1, 0x8000
	v_add_u32_e32 v5, 0x410, v4
	v_add_u32_e32 v14, 0x618, v4
	v_add_u32_e32 v63, 0x820, v4
	v_add_u32_e32 v72, 0xa28, v4
	v_add_u32_e32 v73, 0xc30, v4
	v_add_u32_e32 v74, 0xe38, v4
	s_waitcnt vmcnt(31)
	ds_write2_b32 v4, v6, v7 offset1:1
	s_waitcnt vmcnt(30)
	ds_write2_b32 v4, v8, v9 offset0:130 offset1:131
	v_add_u32_e32 v4, 0x1040, v4
	s_waitcnt vmcnt(29)
	ds_write2_b32 v5, v10, v11 offset1:1
	s_waitcnt vmcnt(28)
	ds_write2_b32 v14, v12, v13 offset1:1
	s_waitcnt vmcnt(27)
	ds_write2_b32 v63, v64, v65 offset1:1
	s_waitcnt vmcnt(26)
	ds_write2_b32 v72, v66, v67 offset1:1
	s_waitcnt vmcnt(25)
	ds_write2_b32 v73, v68, v69 offset1:1
	s_waitcnt vmcnt(24)
	ds_write2_b32 v74, v70, v71 offset1:1
	v_add_u32_e32 v5, 0x410, v4
	v_add_u32_e32 v14, 0x618, v4
	v_add_u32_e32 v63, 0x820, v4
	v_add_u32_e32 v72, 0xa28, v4
	v_add_u32_e32 v73, 0xc30, v4
	v_add_u32_e32 v74, 0xe38, v4
	s_waitcnt vmcnt(23)
	ds_write2_b32 v4, v150, v151 offset1:1
	s_waitcnt vmcnt(22)
	ds_write2_b32 v4, v152, v153 offset0:130 offset1:131
	v_add_u32_e32 v4, 0x1040, v4
	s_waitcnt vmcnt(21)
	ds_write2_b32 v5, v154, v155 offset1:1
	s_waitcnt vmcnt(20)
	ds_write2_b32 v14, v156, v157 offset1:1
	s_waitcnt vmcnt(19)
	ds_write2_b32 v63, v158, v159 offset1:1
	s_waitcnt vmcnt(18)
	ds_write2_b32 v72, v160, v161 offset1:1
	s_waitcnt vmcnt(17)
	ds_write2_b32 v73, v162, v163 offset1:1
	s_waitcnt vmcnt(16)
	ds_write2_b32 v74, v164, v165 offset1:1
	v_add_u32_e32 v5, 0x410, v4
	v_add_u32_e32 v14, 0x618, v4
	v_add_u32_e32 v63, 0x820, v4
	v_add_u32_e32 v72, 0xa28, v4
	v_add_u32_e32 v73, 0xc30, v4
	v_add_u32_e32 v74, 0xe38, v4
	s_waitcnt vmcnt(15)
	ds_write2_b32 v4, v166, v167 offset1:1
	s_waitcnt vmcnt(14)
	ds_write2_b32 v4, v168, v169 offset0:130 offset1:131
	v_add_u32_e32 v4, 0x1040, v4
	s_waitcnt vmcnt(13)
	ds_write2_b32 v5, v170, v171 offset1:1
	s_waitcnt vmcnt(12)
	ds_write2_b32 v14, v172, v173 offset1:1
	s_waitcnt vmcnt(11)
	ds_write2_b32 v63, v174, v175 offset1:1
	s_waitcnt vmcnt(10)
	ds_write2_b32 v72, v176, v177 offset1:1
	s_waitcnt vmcnt(9)
	ds_write2_b32 v73, v178, v179 offset1:1
	s_waitcnt vmcnt(8)
	ds_write2_b32 v74, v180, v181 offset1:1
	v_add_u32_e32 v5, 0x410, v4
	v_add_u32_e32 v14, 0x618, v4
	v_add_u32_e32 v63, 0x820, v4
	v_add_u32_e32 v72, 0xa28, v4
	v_add_u32_e32 v73, 0xc30, v4
	v_add_u32_e32 v74, 0xe38, v4
	s_waitcnt vmcnt(7)
	ds_write2_b32 v4, v182, v183 offset1:1
	s_waitcnt vmcnt(6)
	ds_write2_b32 v4, v184, v185 offset0:130 offset1:131
	v_add_u32_e32 v4, 0x1040, v4
	s_waitcnt vmcnt(5)
	ds_write2_b32 v5, v186, v187 offset1:1
	s_waitcnt vmcnt(4)
	ds_write2_b32 v14, v188, v189 offset1:1
	s_waitcnt vmcnt(3)
	ds_write2_b32 v63, v190, v191 offset1:1
	s_waitcnt vmcnt(2)
	ds_write2_b32 v72, v192, v193 offset1:1
	s_waitcnt vmcnt(1)
	ds_write2_b32 v73, v194, v195 offset1:1
	s_waitcnt vmcnt(0)
	ds_write2_b32 v74, v196, v197 offset1:1
	s_waitcnt lgkmcnt(0)
	ds_read2_b32 v[2:3], v81 offset1:65
	s_waitcnt lgkmcnt(0)
	v_cvt_pk_bf16_f32 v2, v2, v3
	ds_read2_b32 v[4:5], v81 offset0:130 offset1:195
	v_add_u32_e32 v12, 0x400, v81
	s_lshl_b32 s1, s96, 1
	s_waitcnt lgkmcnt(0)
	v_cvt_pk_bf16_f32 v3, v4, v5
	ds_read2_b32 v[4:5], v12 offset0:4 offset1:69
	s_and_b32 s1, s1, 0x3fc0
	s_waitcnt lgkmcnt(0)
	v_cvt_pk_bf16_f32 v4, v4, v5
	v_or_b32_e32 v5, s0, v80
	s_add_i32 s8, s1, 0xffffca40
	v_lshlrev_b32_e32 v14, 12, v5
	v_lshl_add_u64 v[8:9], s[8:9], 1, v[28:29]
	ds_read2_b32 v[6:7], v12 offset0:134 offset1:199
	s_waitcnt lgkmcnt(0)
	v_cvt_pk_bf16_f32 v5, v6, v7
	v_lshl_add_u64 v[10:11], v[8:9], 0, v[14:15]
	ds_read2_b32 v[6:7], v81 offset0:8 offset1:73
	global_store_dwordx4 v[10:11], v[2:5], off
	v_or_b32_e32 v10, s0, v82
	v_lshlrev_b32_e32 v14, 12, v10
	s_waitcnt lgkmcnt(0)
	v_cvt_pk_bf16_f32 v2, v6, v7
	ds_read2_b32 v[4:5], v81 offset0:138 offset1:203
	s_waitcnt lgkmcnt(0)
	v_cvt_pk_bf16_f32 v3, v4, v5
	ds_read2_b32 v[4:5], v12 offset0:12 offset1:77
	s_waitcnt lgkmcnt(0)
	v_cvt_pk_bf16_f32 v4, v4, v5
	ds_read2_b32 v[6:7], v12 offset0:142 offset1:207
	s_waitcnt lgkmcnt(0)
	v_cvt_pk_bf16_f32 v5, v6, v7
	v_lshl_add_u64 v[10:11], v[8:9], 0, v[14:15]
	ds_read2_b32 v[6:7], v81 offset0:16 offset1:81
	global_store_dwordx4 v[10:11], v[2:5], off
	v_or_b32_e32 v10, s0, v83
	v_lshlrev_b32_e32 v14, 12, v10
	s_waitcnt lgkmcnt(0)
	v_cvt_pk_bf16_f32 v2, v6, v7
	ds_read2_b32 v[4:5], v81 offset0:146 offset1:211
	s_waitcnt lgkmcnt(0)
	v_cvt_pk_bf16_f32 v3, v4, v5
	ds_read2_b32 v[4:5], v12 offset0:20 offset1:85
	s_waitcnt lgkmcnt(0)
	v_cvt_pk_bf16_f32 v4, v4, v5
	ds_read2_b32 v[6:7], v12 offset0:150 offset1:215
	s_waitcnt lgkmcnt(0)
	v_cvt_pk_bf16_f32 v5, v6, v7
	v_lshl_add_u64 v[10:11], v[8:9], 0, v[14:15]
	ds_read2_b32 v[6:7], v81 offset0:24 offset1:89
	global_store_dwordx4 v[10:11], v[2:5], off
	v_or_b32_e32 v10, s0, v84
	v_lshlrev_b32_e32 v14, 12, v10
	s_waitcnt lgkmcnt(0)
	v_cvt_pk_bf16_f32 v2, v6, v7
	ds_read2_b32 v[4:5], v81 offset0:154 offset1:219
	s_waitcnt lgkmcnt(0)
	v_cvt_pk_bf16_f32 v3, v4, v5
	ds_read2_b32 v[4:5], v12 offset0:28 offset1:93
	s_waitcnt lgkmcnt(0)
	v_cvt_pk_bf16_f32 v4, v4, v5
	ds_read2_b32 v[6:7], v12 offset0:158 offset1:223
	s_waitcnt lgkmcnt(0)
	v_cvt_pk_bf16_f32 v5, v6, v7
	v_lshl_add_u64 v[10:11], v[8:9], 0, v[14:15]
	ds_read2_b32 v[6:7], v81 offset0:32 offset1:97
	global_store_dwordx4 v[10:11], v[2:5], off
	v_or_b32_e32 v10, s0, v85
	v_lshlrev_b32_e32 v14, 12, v10
	s_waitcnt lgkmcnt(0)
	v_cvt_pk_bf16_f32 v2, v6, v7
	ds_read2_b32 v[4:5], v81 offset0:162 offset1:227
	s_waitcnt lgkmcnt(0)
	v_cvt_pk_bf16_f32 v3, v4, v5
	ds_read2_b32 v[4:5], v12 offset0:36 offset1:101
	s_waitcnt lgkmcnt(0)
	v_cvt_pk_bf16_f32 v4, v4, v5
	ds_read2_b32 v[6:7], v12 offset0:166 offset1:231
	s_waitcnt lgkmcnt(0)
	v_cvt_pk_bf16_f32 v5, v6, v7
	v_lshl_add_u64 v[10:11], v[8:9], 0, v[14:15]
	ds_read2_b32 v[6:7], v81 offset0:40 offset1:105
	global_store_dwordx4 v[10:11], v[2:5], off
	v_or_b32_e32 v10, s0, v86
	v_lshlrev_b32_e32 v14, 12, v10
	s_waitcnt lgkmcnt(0)
	v_cvt_pk_bf16_f32 v2, v6, v7
	ds_read2_b32 v[4:5], v81 offset0:170 offset1:235
	s_waitcnt lgkmcnt(0)
	v_cvt_pk_bf16_f32 v3, v4, v5
	ds_read2_b32 v[4:5], v12 offset0:44 offset1:109
	s_waitcnt lgkmcnt(0)
	v_cvt_pk_bf16_f32 v4, v4, v5
	ds_read2_b32 v[6:7], v12 offset0:174 offset1:239
	s_waitcnt lgkmcnt(0)
	v_cvt_pk_bf16_f32 v5, v6, v7
	v_lshl_add_u64 v[10:11], v[8:9], 0, v[14:15]
	ds_read2_b32 v[6:7], v81 offset0:48 offset1:113
	global_store_dwordx4 v[10:11], v[2:5], off
	v_or_b32_e32 v10, s0, v87
	v_lshlrev_b32_e32 v14, 12, v10
	s_waitcnt lgkmcnt(0)
	v_cvt_pk_bf16_f32 v2, v6, v7
	ds_read2_b32 v[4:5], v81 offset0:178 offset1:243
	s_waitcnt lgkmcnt(0)
	v_cvt_pk_bf16_f32 v3, v4, v5
	ds_read2_b32 v[4:5], v12 offset0:52 offset1:117
	s_waitcnt lgkmcnt(0)
	v_cvt_pk_bf16_f32 v4, v4, v5
	ds_read2_b32 v[6:7], v12 offset0:182 offset1:247
	s_waitcnt lgkmcnt(0)
	v_cvt_pk_bf16_f32 v5, v6, v7
	v_lshl_add_u64 v[10:11], v[8:9], 0, v[14:15]
	ds_read2_b32 v[6:7], v81 offset0:56 offset1:121
	global_store_dwordx4 v[10:11], v[2:5], off
	s_waitcnt lgkmcnt(0)
	s_nop 0
	v_cvt_pk_bf16_f32 v2, v6, v7
	ds_read2_b32 v[4:5], v81 offset0:186 offset1:251
	s_waitcnt lgkmcnt(0)
	v_cvt_pk_bf16_f32 v3, v4, v5
	ds_read2_b32 v[4:5], v12 offset0:60 offset1:125
	s_waitcnt lgkmcnt(0)
	v_cvt_pk_bf16_f32 v4, v4, v5
	v_or_b32_e32 v5, s0, v88
	ds_read2_b32 v[6:7], v12 offset0:190 offset1:255
	v_lshlrev_b32_e32 v14, 12, v5
	s_waitcnt lgkmcnt(0)
	v_cvt_pk_bf16_f32 v5, v6, v7
	v_lshl_add_u64 v[6:7], v[8:9], 0, v[14:15]
	global_store_dwordx4 v[6:7], v[2:5], off
	s_waitcnt lgkmcnt(0)

.LBB0_55:
	v_add_u32_e32 v5, s1, v62
	v_add_u32_e32 v14, 0xfe720000, v5
	v_lshl_add_u64 v[6:7], v[14:15], 2, v[2:3]
	v_add_u32_e32 v14, 0xfe721000, v5
	v_lshl_add_u64 v[8:9], v[14:15], 2, v[2:3]
	v_add_u32_e32 v14, 0xfe722000, v5
	v_lshl_add_u64 v[10:11], v[14:15], 2, v[2:3]
	v_add_u32_e32 v14, 0xfe723000, v5
	v_lshl_add_u64 v[12:13], v[14:15], 2, v[2:3]
	v_add_u32_e32 v14, 0xfe724000, v5
	v_lshl_add_u64 v[64:65], v[14:15], 2, v[2:3]
	v_add_u32_e32 v14, 0xfe725000, v5
	v_lshl_add_u64 v[66:67], v[14:15], 2, v[2:3]
	v_add_u32_e32 v14, 0xfe726000, v5
	v_lshl_add_u64 v[68:69], v[14:15], 2, v[2:3]
	v_add_u32_e32 v14, 0xfe727000, v5
	global_load_dwordx2 v[6:7], v[6:7], off
	s_nop 0
	global_load_dwordx2 v[8:9], v[8:9], off
	v_lshl_add_u64 v[70:71], v[14:15], 2, v[2:3]
	global_load_dwordx2 v[10:11], v[10:11], off
	s_nop 0
	global_load_dwordx2 v[12:13], v[12:13], off
	s_nop 0
	global_load_dwordx2 v[64:65], v[64:65], off
	s_nop 0
	global_load_dwordx2 v[66:67], v[66:67], off
	s_nop 0
	global_load_dwordx2 v[68:69], v[68:69], off
	s_nop 0
	global_load_dwordx2 v[70:71], v[70:71], off
	s_add_i32 s1, s1, 0x8000
	v_add_u32_e32 v5, s1, v62
	v_add_u32_e32 v14, 0xfe720000, v5
	v_lshl_add_u64 v[150:151], v[14:15], 2, v[2:3]
	v_add_u32_e32 v14, 0xfe721000, v5
	v_lshl_add_u64 v[152:153], v[14:15], 2, v[2:3]
	v_add_u32_e32 v14, 0xfe722000, v5
	v_lshl_add_u64 v[154:155], v[14:15], 2, v[2:3]
	v_add_u32_e32 v14, 0xfe723000, v5
	v_lshl_add_u64 v[156:157], v[14:15], 2, v[2:3]
	v_add_u32_e32 v14, 0xfe724000, v5
	v_lshl_add_u64 v[158:159], v[14:15], 2, v[2:3]
	v_add_u32_e32 v14, 0xfe725000, v5
	v_lshl_add_u64 v[160:161], v[14:15], 2, v[2:3]
	v_add_u32_e32 v14, 0xfe726000, v5
	v_lshl_add_u64 v[162:163], v[14:15], 2, v[2:3]
	v_add_u32_e32 v14, 0xfe727000, v5
	global_load_dwordx2 v[150:151], v[150:151], off
	s_nop 0
	global_load_dwordx2 v[152:153], v[152:153], off
	v_lshl_add_u64 v[164:165], v[14:15], 2, v[2:3]
	global_load_dwordx2 v[154:155], v[154:155], off
	s_nop 0
	global_load_dwordx2 v[156:157], v[156:157], off
	s_nop 0
	global_load_dwordx2 v[158:159], v[158:159], off
	s_nop 0
	global_load_dwordx2 v[160:161], v[160:161], off
	s_nop 0
	global_load_dwordx2 v[162:163], v[162:163], off
	s_nop 0
	global_load_dwordx2 v[164:165], v[164:165], off
	s_add_i32 s1, s1, 0x8000
	v_add_u32_e32 v5, s1, v62
	v_add_u32_e32 v14, 0xfe720000, v5
	v_lshl_add_u64 v[166:167], v[14:15], 2, v[2:3]
	v_add_u32_e32 v14, 0xfe721000, v5
	v_lshl_add_u64 v[168:169], v[14:15], 2, v[2:3]
	v_add_u32_e32 v14, 0xfe722000, v5
	v_lshl_add_u64 v[170:171], v[14:15], 2, v[2:3]
	v_add_u32_e32 v14, 0xfe723000, v5
	v_lshl_add_u64 v[172:173], v[14:15], 2, v[2:3]
	v_add_u32_e32 v14, 0xfe724000, v5
	v_lshl_add_u64 v[174:175], v[14:15], 2, v[2:3]
	v_add_u32_e32 v14, 0xfe725000, v5
	v_lshl_add_u64 v[176:177], v[14:15], 2, v[2:3]
	v_add_u32_e32 v14, 0xfe726000, v5
	v_lshl_add_u64 v[178:179], v[14:15], 2, v[2:3]
	v_add_u32_e32 v14, 0xfe727000, v5
	global_load_dwordx2 v[166:167], v[166:167], off
	s_nop 0
	global_load_dwordx2 v[168:169], v[168:169], off
	v_lshl_add_u64 v[180:181], v[14:15], 2, v[2:3]
	global_load_dwordx2 v[170:171], v[170:171], off
	s_nop 0
	global_load_dwordx2 v[172:173], v[172:173], off
	s_nop 0
	global_load_dwordx2 v[174:175], v[174:175], off
	s_nop 0
	global_load_dwordx2 v[176:177], v[176:177], off
	s_nop 0
	global_load_dwordx2 v[178:179], v[178:179], off
	s_nop 0
	global_load_dwordx2 v[180:181], v[180:181], off
	s_add_i32 s1, s1, 0x8000
	v_add_u32_e32 v5, s1, v62
	v_add_u32_e32 v14, 0xfe720000, v5
	v_lshl_add_u64 v[182:183], v[14:15], 2, v[2:3]
	v_add_u32_e32 v14, 0xfe721000, v5
	v_lshl_add_u64 v[184:185], v[14:15], 2, v[2:3]
	v_add_u32_e32 v14, 0xfe722000, v5
	v_lshl_add_u64 v[186:187], v[14:15], 2, v[2:3]
	v_add_u32_e32 v14, 0xfe723000, v5
	v_lshl_add_u64 v[188:189], v[14:15], 2, v[2:3]
	v_add_u32_e32 v14, 0xfe724000, v5
	v_lshl_add_u64 v[190:191], v[14:15], 2, v[2:3]
	v_add_u32_e32 v14, 0xfe725000, v5
	v_lshl_add_u64 v[192:193], v[14:15], 2, v[2:3]
	v_add_u32_e32 v14, 0xfe726000, v5
	v_lshl_add_u64 v[194:195], v[14:15], 2, v[2:3]
	v_add_u32_e32 v14, 0xfe727000, v5
	global_load_dwordx2 v[182:183], v[182:183], off
	s_nop 0
	global_load_dwordx2 v[184:185], v[184:185], off
	v_lshl_add_u64 v[196:197], v[14:15], 2, v[2:3]
	global_load_dwordx2 v[186:187], v[186:187], off
	s_nop 0
	global_load_dwordx2 v[188:189], v[188:189], off
	s_nop 0
	global_load_dwordx2 v[190:191], v[190:191], off
	s_nop 0
	global_load_dwordx2 v[192:193], v[192:193], off
	s_nop 0
	global_load_dwordx2 v[194:195], v[194:195], off
	s_nop 0
	global_load_dwordx2 v[196:197], v[196:197], off
	s_add_i32 s1, s1, 0x8000
	v_add_u32_e32 v5, 0x410, v4
	v_add_u32_e32 v14, 0x618, v4
	v_add_u32_e32 v63, 0x820, v4
	v_add_u32_e32 v72, 0xa28, v4
	v_add_u32_e32 v73, 0xc30, v4
	v_add_u32_e32 v74, 0xe38, v4
	s_waitcnt vmcnt(31)
	ds_write2_b32 v4, v6, v7 offset1:1
	s_waitcnt vmcnt(30)
	ds_write2_b32 v4, v8, v9 offset0:130 offset1:131
	v_add_u32_e32 v4, 0x1040, v4
	s_waitcnt vmcnt(29)
	ds_write2_b32 v5, v10, v11 offset1:1
	s_waitcnt vmcnt(28)
	ds_write2_b32 v14, v12, v13 offset1:1
	s_waitcnt vmcnt(27)
	ds_write2_b32 v63, v64, v65 offset1:1
	s_waitcnt vmcnt(26)
	ds_write2_b32 v72, v66, v67 offset1:1
	s_waitcnt vmcnt(25)
	ds_write2_b32 v73, v68, v69 offset1:1
	s_waitcnt vmcnt(24)
	ds_write2_b32 v74, v70, v71 offset1:1
	v_add_u32_e32 v5, 0x410, v4
	v_add_u32_e32 v14, 0x618, v4
	v_add_u32_e32 v63, 0x820, v4
	v_add_u32_e32 v72, 0xa28, v4
	v_add_u32_e32 v73, 0xc30, v4
	v_add_u32_e32 v74, 0xe38, v4
	s_waitcnt vmcnt(23)
	ds_write2_b32 v4, v150, v151 offset1:1
	s_waitcnt vmcnt(22)
	ds_write2_b32 v4, v152, v153 offset0:130 offset1:131
	v_add_u32_e32 v4, 0x1040, v4
	s_waitcnt vmcnt(21)
	ds_write2_b32 v5, v154, v155 offset1:1
	s_waitcnt vmcnt(20)
	ds_write2_b32 v14, v156, v157 offset1:1
	s_waitcnt vmcnt(19)
	ds_write2_b32 v63, v158, v159 offset1:1
	s_waitcnt vmcnt(18)
	ds_write2_b32 v72, v160, v161 offset1:1
	s_waitcnt vmcnt(17)
	ds_write2_b32 v73, v162, v163 offset1:1
	s_waitcnt vmcnt(16)
	ds_write2_b32 v74, v164, v165 offset1:1
	v_add_u32_e32 v5, 0x410, v4
	v_add_u32_e32 v14, 0x618, v4
	v_add_u32_e32 v63, 0x820, v4
	v_add_u32_e32 v72, 0xa28, v4
	v_add_u32_e32 v73, 0xc30, v4
	v_add_u32_e32 v74, 0xe38, v4
	s_waitcnt vmcnt(15)
	ds_write2_b32 v4, v166, v167 offset1:1
	s_waitcnt vmcnt(14)
	ds_write2_b32 v4, v168, v169 offset0:130 offset1:131
	v_add_u32_e32 v4, 0x1040, v4
	s_waitcnt vmcnt(13)
	ds_write2_b32 v5, v170, v171 offset1:1
	s_waitcnt vmcnt(12)
	ds_write2_b32 v14, v172, v173 offset1:1
	s_waitcnt vmcnt(11)
	ds_write2_b32 v63, v174, v175 offset1:1
	s_waitcnt vmcnt(10)
	ds_write2_b32 v72, v176, v177 offset1:1
	s_waitcnt vmcnt(9)
	ds_write2_b32 v73, v178, v179 offset1:1
	s_waitcnt vmcnt(8)
	ds_write2_b32 v74, v180, v181 offset1:1
	v_add_u32_e32 v5, 0x410, v4
	v_add_u32_e32 v14, 0x618, v4
	v_add_u32_e32 v63, 0x820, v4
	v_add_u32_e32 v72, 0xa28, v4
	v_add_u32_e32 v73, 0xc30, v4
	v_add_u32_e32 v74, 0xe38, v4
	s_waitcnt vmcnt(7)
	ds_write2_b32 v4, v182, v183 offset1:1
	s_waitcnt vmcnt(6)
	ds_write2_b32 v4, v184, v185 offset0:130 offset1:131
	v_add_u32_e32 v4, 0x1040, v4
	s_waitcnt vmcnt(5)
	ds_write2_b32 v5, v186, v187 offset1:1
	s_waitcnt vmcnt(4)
	ds_write2_b32 v14, v188, v189 offset1:1
	s_waitcnt vmcnt(3)
	ds_write2_b32 v63, v190, v191 offset1:1
	s_waitcnt vmcnt(2)
	ds_write2_b32 v72, v192, v193 offset1:1
	s_waitcnt vmcnt(1)
	ds_write2_b32 v73, v194, v195 offset1:1
	s_waitcnt vmcnt(0)
	ds_write2_b32 v74, v196, v197 offset1:1
	s_waitcnt lgkmcnt(0)
	ds_read2_b32 v[2:3], v81 offset1:65
	s_waitcnt lgkmcnt(0)
	v_cvt_pk_bf16_f32 v2, v2, v3
	ds_read2_b32 v[4:5], v81 offset0:130 offset1:195
	v_add_u32_e32 v12, 0x400, v81
	s_lshl_b32 s1, s96, 1
	s_waitcnt lgkmcnt(0)
	v_cvt_pk_bf16_f32 v3, v4, v5
	ds_read2_b32 v[4:5], v12 offset0:4 offset1:69
	s_and_b32 s1, s1, 0x3fc0
	s_waitcnt lgkmcnt(0)
	v_cvt_pk_bf16_f32 v4, v4, v5
	v_or_b32_e32 v5, s0, v80
	s_add_i32 s8, s1, 0xffffce40
	v_lshlrev_b32_e32 v14, 11, v5
	v_lshl_add_u64 v[8:9], s[8:9], 1, v[32:33]
	ds_read2_b32 v[6:7], v12 offset0:134 offset1:199
	s_waitcnt lgkmcnt(0)
	v_cvt_pk_bf16_f32 v5, v6, v7
	v_lshl_add_u64 v[10:11], v[8:9], 0, v[14:15]
	ds_read2_b32 v[6:7], v81 offset0:8 offset1:73
	global_store_dwordx4 v[10:11], v[2:5], off
	v_or_b32_e32 v10, s0, v82
	v_lshlrev_b32_e32 v14, 11, v10
	s_waitcnt lgkmcnt(0)
	v_cvt_pk_bf16_f32 v2, v6, v7
	ds_read2_b32 v[4:5], v81 offset0:138 offset1:203
	s_waitcnt lgkmcnt(0)
	v_cvt_pk_bf16_f32 v3, v4, v5
	ds_read2_b32 v[4:5], v12 offset0:12 offset1:77
	s_waitcnt lgkmcnt(0)
	v_cvt_pk_bf16_f32 v4, v4, v5
	ds_read2_b32 v[6:7], v12 offset0:142 offset1:207
	s_waitcnt lgkmcnt(0)
	v_cvt_pk_bf16_f32 v5, v6, v7
	v_lshl_add_u64 v[10:11], v[8:9], 0, v[14:15]
	ds_read2_b32 v[6:7], v81 offset0:16 offset1:81
	global_store_dwordx4 v[10:11], v[2:5], off
	v_or_b32_e32 v10, s0, v83
	v_lshlrev_b32_e32 v14, 11, v10
	s_waitcnt lgkmcnt(0)
	v_cvt_pk_bf16_f32 v2, v6, v7
	ds_read2_b32 v[4:5], v81 offset0:146 offset1:211
	s_waitcnt lgkmcnt(0)
	v_cvt_pk_bf16_f32 v3, v4, v5
	ds_read2_b32 v[4:5], v12 offset0:20 offset1:85
	s_waitcnt lgkmcnt(0)
	v_cvt_pk_bf16_f32 v4, v4, v5
	ds_read2_b32 v[6:7], v12 offset0:150 offset1:215
	s_waitcnt lgkmcnt(0)
	v_cvt_pk_bf16_f32 v5, v6, v7
	v_lshl_add_u64 v[10:11], v[8:9], 0, v[14:15]
	ds_read2_b32 v[6:7], v81 offset0:24 offset1:89
	global_store_dwordx4 v[10:11], v[2:5], off
	v_or_b32_e32 v10, s0, v84
	v_lshlrev_b32_e32 v14, 11, v10
	s_waitcnt lgkmcnt(0)
	v_cvt_pk_bf16_f32 v2, v6, v7
	ds_read2_b32 v[4:5], v81 offset0:154 offset1:219
	s_waitcnt lgkmcnt(0)
	v_cvt_pk_bf16_f32 v3, v4, v5
	ds_read2_b32 v[4:5], v12 offset0:28 offset1:93
	s_waitcnt lgkmcnt(0)
	v_cvt_pk_bf16_f32 v4, v4, v5
	ds_read2_b32 v[6:7], v12 offset0:158 offset1:223
	s_waitcnt lgkmcnt(0)
	v_cvt_pk_bf16_f32 v5, v6, v7
	v_lshl_add_u64 v[10:11], v[8:9], 0, v[14:15]
	ds_read2_b32 v[6:7], v81 offset0:32 offset1:97
	global_store_dwordx4 v[10:11], v[2:5], off
	v_or_b32_e32 v10, s0, v85
	v_lshlrev_b32_e32 v14, 11, v10
	s_waitcnt lgkmcnt(0)
	v_cvt_pk_bf16_f32 v2, v6, v7
	ds_read2_b32 v[4:5], v81 offset0:162 offset1:227
	s_waitcnt lgkmcnt(0)
	v_cvt_pk_bf16_f32 v3, v4, v5
	ds_read2_b32 v[4:5], v12 offset0:36 offset1:101
	s_waitcnt lgkmcnt(0)
	v_cvt_pk_bf16_f32 v4, v4, v5
	ds_read2_b32 v[6:7], v12 offset0:166 offset1:231
	s_waitcnt lgkmcnt(0)
	v_cvt_pk_bf16_f32 v5, v6, v7
	v_lshl_add_u64 v[10:11], v[8:9], 0, v[14:15]
	ds_read2_b32 v[6:7], v81 offset0:40 offset1:105
	global_store_dwordx4 v[10:11], v[2:5], off
	v_or_b32_e32 v10, s0, v86
	v_lshlrev_b32_e32 v14, 11, v10
	s_waitcnt lgkmcnt(0)
	v_cvt_pk_bf16_f32 v2, v6, v7
	ds_read2_b32 v[4:5], v81 offset0:170 offset1:235
	s_waitcnt lgkmcnt(0)
	v_cvt_pk_bf16_f32 v3, v4, v5
	ds_read2_b32 v[4:5], v12 offset0:44 offset1:109
	s_waitcnt lgkmcnt(0)
	v_cvt_pk_bf16_f32 v4, v4, v5
	ds_read2_b32 v[6:7], v12 offset0:174 offset1:239
	s_waitcnt lgkmcnt(0)
	v_cvt_pk_bf16_f32 v5, v6, v7
	v_lshl_add_u64 v[10:11], v[8:9], 0, v[14:15]
	ds_read2_b32 v[6:7], v81 offset0:48 offset1:113
	global_store_dwordx4 v[10:11], v[2:5], off
	v_or_b32_e32 v10, s0, v87
	v_lshlrev_b32_e32 v14, 11, v10
	s_waitcnt lgkmcnt(0)
	v_cvt_pk_bf16_f32 v2, v6, v7
	ds_read2_b32 v[4:5], v81 offset0:178 offset1:243
	s_waitcnt lgkmcnt(0)
	v_cvt_pk_bf16_f32 v3, v4, v5
	ds_read2_b32 v[4:5], v12 offset0:52 offset1:117
	s_waitcnt lgkmcnt(0)
	v_cvt_pk_bf16_f32 v4, v4, v5
	ds_read2_b32 v[6:7], v12 offset0:182 offset1:247
	s_waitcnt lgkmcnt(0)
	v_cvt_pk_bf16_f32 v5, v6, v7
	v_lshl_add_u64 v[10:11], v[8:9], 0, v[14:15]
	ds_read2_b32 v[6:7], v81 offset0:56 offset1:121
	global_store_dwordx4 v[10:11], v[2:5], off
	s_waitcnt lgkmcnt(0)
	s_nop 0
	v_cvt_pk_bf16_f32 v2, v6, v7
	ds_read2_b32 v[4:5], v81 offset0:186 offset1:251
	s_waitcnt lgkmcnt(0)
	v_cvt_pk_bf16_f32 v3, v4, v5
	ds_read2_b32 v[4:5], v12 offset0:60 offset1:125
	s_waitcnt lgkmcnt(0)
	v_cvt_pk_bf16_f32 v4, v4, v5
	v_or_b32_e32 v5, s0, v88
	ds_read2_b32 v[6:7], v12 offset0:190 offset1:255
	v_lshlrev_b32_e32 v14, 11, v5
	s_waitcnt lgkmcnt(0)
	v_cvt_pk_bf16_f32 v5, v6, v7
	v_lshl_add_u64 v[6:7], v[8:9], 0, v[14:15]
	global_store_dwordx4 v[6:7], v[2:5], off
	s_waitcnt lgkmcnt(0)

.LBB0_60:
	v_add_u32_e32 v5, s1, v62
	v_add_u32_e32 v14, 0xfe920000, v5
	v_lshl_add_u64 v[6:7], v[14:15], 2, v[2:3]
	v_add_u32_e32 v14, 0xfe921000, v5
	v_lshl_add_u64 v[8:9], v[14:15], 2, v[2:3]
	v_add_u32_e32 v14, 0xfe922000, v5
	v_lshl_add_u64 v[10:11], v[14:15], 2, v[2:3]
	v_add_u32_e32 v14, 0xfe923000, v5
	v_lshl_add_u64 v[12:13], v[14:15], 2, v[2:3]
	v_add_u32_e32 v14, 0xfe924000, v5
	v_lshl_add_u64 v[64:65], v[14:15], 2, v[2:3]
	v_add_u32_e32 v14, 0xfe925000, v5
	v_lshl_add_u64 v[66:67], v[14:15], 2, v[2:3]
	v_add_u32_e32 v14, 0xfe926000, v5
	v_lshl_add_u64 v[68:69], v[14:15], 2, v[2:3]
	v_add_u32_e32 v14, 0xfe927000, v5
	global_load_dwordx2 v[6:7], v[6:7], off
	s_nop 0
	global_load_dwordx2 v[8:9], v[8:9], off
	v_lshl_add_u64 v[70:71], v[14:15], 2, v[2:3]
	global_load_dwordx2 v[10:11], v[10:11], off
	s_nop 0
	global_load_dwordx2 v[12:13], v[12:13], off
	s_nop 0
	global_load_dwordx2 v[64:65], v[64:65], off
	s_nop 0
	global_load_dwordx2 v[66:67], v[66:67], off
	s_nop 0
	global_load_dwordx2 v[68:69], v[68:69], off
	s_nop 0
	global_load_dwordx2 v[70:71], v[70:71], off
	s_add_i32 s1, s1, 0x8000
	v_add_u32_e32 v5, s1, v62
	v_add_u32_e32 v14, 0xfe920000, v5
	v_lshl_add_u64 v[150:151], v[14:15], 2, v[2:3]
	v_add_u32_e32 v14, 0xfe921000, v5
	v_lshl_add_u64 v[152:153], v[14:15], 2, v[2:3]
	v_add_u32_e32 v14, 0xfe922000, v5
	v_lshl_add_u64 v[154:155], v[14:15], 2, v[2:3]
	v_add_u32_e32 v14, 0xfe923000, v5
	v_lshl_add_u64 v[156:157], v[14:15], 2, v[2:3]
	v_add_u32_e32 v14, 0xfe924000, v5
	v_lshl_add_u64 v[158:159], v[14:15], 2, v[2:3]
	v_add_u32_e32 v14, 0xfe925000, v5
	v_lshl_add_u64 v[160:161], v[14:15], 2, v[2:3]
	v_add_u32_e32 v14, 0xfe926000, v5
	v_lshl_add_u64 v[162:163], v[14:15], 2, v[2:3]
	v_add_u32_e32 v14, 0xfe927000, v5
	global_load_dwordx2 v[150:151], v[150:151], off
	s_nop 0
	global_load_dwordx2 v[152:153], v[152:153], off
	v_lshl_add_u64 v[164:165], v[14:15], 2, v[2:3]
	global_load_dwordx2 v[154:155], v[154:155], off
	s_nop 0
	global_load_dwordx2 v[156:157], v[156:157], off
	s_nop 0
	global_load_dwordx2 v[158:159], v[158:159], off
	s_nop 0
	global_load_dwordx2 v[160:161], v[160:161], off
	s_nop 0
	global_load_dwordx2 v[162:163], v[162:163], off
	s_nop 0
	global_load_dwordx2 v[164:165], v[164:165], off
	s_add_i32 s1, s1, 0x8000
	v_add_u32_e32 v5, s1, v62
	v_add_u32_e32 v14, 0xfe920000, v5
	v_lshl_add_u64 v[166:167], v[14:15], 2, v[2:3]
	v_add_u32_e32 v14, 0xfe921000, v5
	v_lshl_add_u64 v[168:169], v[14:15], 2, v[2:3]
	v_add_u32_e32 v14, 0xfe922000, v5
	v_lshl_add_u64 v[170:171], v[14:15], 2, v[2:3]
	v_add_u32_e32 v14, 0xfe923000, v5
	v_lshl_add_u64 v[172:173], v[14:15], 2, v[2:3]
	v_add_u32_e32 v14, 0xfe924000, v5
	v_lshl_add_u64 v[174:175], v[14:15], 2, v[2:3]
	v_add_u32_e32 v14, 0xfe925000, v5
	v_lshl_add_u64 v[176:177], v[14:15], 2, v[2:3]
	v_add_u32_e32 v14, 0xfe926000, v5
	v_lshl_add_u64 v[178:179], v[14:15], 2, v[2:3]
	v_add_u32_e32 v14, 0xfe927000, v5
	global_load_dwordx2 v[166:167], v[166:167], off
	s_nop 0
	global_load_dwordx2 v[168:169], v[168:169], off
	v_lshl_add_u64 v[180:181], v[14:15], 2, v[2:3]
	global_load_dwordx2 v[170:171], v[170:171], off
	s_nop 0
	global_load_dwordx2 v[172:173], v[172:173], off
	s_nop 0
	global_load_dwordx2 v[174:175], v[174:175], off
	s_nop 0
	global_load_dwordx2 v[176:177], v[176:177], off
	s_nop 0
	global_load_dwordx2 v[178:179], v[178:179], off
	s_nop 0
	global_load_dwordx2 v[180:181], v[180:181], off
	s_add_i32 s1, s1, 0x8000
	v_add_u32_e32 v5, s1, v62
	v_add_u32_e32 v14, 0xfe920000, v5
	v_lshl_add_u64 v[182:183], v[14:15], 2, v[2:3]
	v_add_u32_e32 v14, 0xfe921000, v5
	v_lshl_add_u64 v[184:185], v[14:15], 2, v[2:3]
	v_add_u32_e32 v14, 0xfe922000, v5
	v_lshl_add_u64 v[186:187], v[14:15], 2, v[2:3]
	v_add_u32_e32 v14, 0xfe923000, v5
	v_lshl_add_u64 v[188:189], v[14:15], 2, v[2:3]
	v_add_u32_e32 v14, 0xfe924000, v5
	v_lshl_add_u64 v[190:191], v[14:15], 2, v[2:3]
	v_add_u32_e32 v14, 0xfe925000, v5
	v_lshl_add_u64 v[192:193], v[14:15], 2, v[2:3]
	v_add_u32_e32 v14, 0xfe926000, v5
	v_lshl_add_u64 v[194:195], v[14:15], 2, v[2:3]
	v_add_u32_e32 v14, 0xfe927000, v5
	global_load_dwordx2 v[182:183], v[182:183], off
	s_nop 0
	global_load_dwordx2 v[184:185], v[184:185], off
	v_lshl_add_u64 v[196:197], v[14:15], 2, v[2:3]
	global_load_dwordx2 v[186:187], v[186:187], off
	s_nop 0
	global_load_dwordx2 v[188:189], v[188:189], off
	s_nop 0
	global_load_dwordx2 v[190:191], v[190:191], off
	s_nop 0
	global_load_dwordx2 v[192:193], v[192:193], off
	s_nop 0
	global_load_dwordx2 v[194:195], v[194:195], off
	s_nop 0
	global_load_dwordx2 v[196:197], v[196:197], off
	s_add_i32 s1, s1, 0x8000
	v_add_u32_e32 v5, 0x410, v4
	v_add_u32_e32 v14, 0x618, v4
	v_add_u32_e32 v63, 0x820, v4
	v_add_u32_e32 v72, 0xa28, v4
	v_add_u32_e32 v73, 0xc30, v4
	v_add_u32_e32 v74, 0xe38, v4
	s_waitcnt vmcnt(31)
	ds_write2_b32 v4, v6, v7 offset1:1
	s_waitcnt vmcnt(30)
	ds_write2_b32 v4, v8, v9 offset0:130 offset1:131
	v_add_u32_e32 v4, 0x1040, v4
	s_waitcnt vmcnt(29)
	ds_write2_b32 v5, v10, v11 offset1:1
	s_waitcnt vmcnt(28)
	ds_write2_b32 v14, v12, v13 offset1:1
	s_waitcnt vmcnt(27)
	ds_write2_b32 v63, v64, v65 offset1:1
	s_waitcnt vmcnt(26)
	ds_write2_b32 v72, v66, v67 offset1:1
	s_waitcnt vmcnt(25)
	ds_write2_b32 v73, v68, v69 offset1:1
	s_waitcnt vmcnt(24)
	ds_write2_b32 v74, v70, v71 offset1:1
	v_add_u32_e32 v5, 0x410, v4
	v_add_u32_e32 v14, 0x618, v4
	v_add_u32_e32 v63, 0x820, v4
	v_add_u32_e32 v72, 0xa28, v4
	v_add_u32_e32 v73, 0xc30, v4
	v_add_u32_e32 v74, 0xe38, v4
	s_waitcnt vmcnt(23)
	ds_write2_b32 v4, v150, v151 offset1:1
	s_waitcnt vmcnt(22)
	ds_write2_b32 v4, v152, v153 offset0:130 offset1:131
	v_add_u32_e32 v4, 0x1040, v4
	s_waitcnt vmcnt(21)
	ds_write2_b32 v5, v154, v155 offset1:1
	s_waitcnt vmcnt(20)
	ds_write2_b32 v14, v156, v157 offset1:1
	s_waitcnt vmcnt(19)
	ds_write2_b32 v63, v158, v159 offset1:1
	s_waitcnt vmcnt(18)
	ds_write2_b32 v72, v160, v161 offset1:1
	s_waitcnt vmcnt(17)
	ds_write2_b32 v73, v162, v163 offset1:1
	s_waitcnt vmcnt(16)
	ds_write2_b32 v74, v164, v165 offset1:1
	v_add_u32_e32 v5, 0x410, v4
	v_add_u32_e32 v14, 0x618, v4
	v_add_u32_e32 v63, 0x820, v4
	v_add_u32_e32 v72, 0xa28, v4
	v_add_u32_e32 v73, 0xc30, v4
	v_add_u32_e32 v74, 0xe38, v4
	s_waitcnt vmcnt(15)
	ds_write2_b32 v4, v166, v167 offset1:1
	s_waitcnt vmcnt(14)
	ds_write2_b32 v4, v168, v169 offset0:130 offset1:131
	v_add_u32_e32 v4, 0x1040, v4
	s_waitcnt vmcnt(13)
	ds_write2_b32 v5, v170, v171 offset1:1
	s_waitcnt vmcnt(12)
	ds_write2_b32 v14, v172, v173 offset1:1
	s_waitcnt vmcnt(11)
	ds_write2_b32 v63, v174, v175 offset1:1
	s_waitcnt vmcnt(10)
	ds_write2_b32 v72, v176, v177 offset1:1
	s_waitcnt vmcnt(9)
	ds_write2_b32 v73, v178, v179 offset1:1
	s_waitcnt vmcnt(8)
	ds_write2_b32 v74, v180, v181 offset1:1
	v_add_u32_e32 v5, 0x410, v4
	v_add_u32_e32 v14, 0x618, v4
	v_add_u32_e32 v63, 0x820, v4
	v_add_u32_e32 v72, 0xa28, v4
	v_add_u32_e32 v73, 0xc30, v4
	v_add_u32_e32 v74, 0xe38, v4
	s_waitcnt vmcnt(7)
	ds_write2_b32 v4, v182, v183 offset1:1
	s_waitcnt vmcnt(6)
	ds_write2_b32 v4, v184, v185 offset0:130 offset1:131
	v_add_u32_e32 v4, 0x1040, v4
	s_waitcnt vmcnt(5)
	ds_write2_b32 v5, v186, v187 offset1:1
	s_waitcnt vmcnt(4)
	ds_write2_b32 v14, v188, v189 offset1:1
	s_waitcnt vmcnt(3)
	ds_write2_b32 v63, v190, v191 offset1:1
	s_waitcnt vmcnt(2)
	ds_write2_b32 v72, v192, v193 offset1:1
	s_waitcnt vmcnt(1)
	ds_write2_b32 v73, v194, v195 offset1:1
	s_waitcnt vmcnt(0)
	ds_write2_b32 v74, v196, v197 offset1:1
	s_waitcnt lgkmcnt(0)
	ds_read2_b32 v[2:3], v81 offset1:65
	s_waitcnt lgkmcnt(0)
	v_cvt_pk_bf16_f32 v2, v2, v3
	ds_read2_b32 v[4:5], v81 offset0:130 offset1:195
	v_add_u32_e32 v12, 0x400, v81
	s_lshl_b32 s1, s96, 1
	s_waitcnt lgkmcnt(0)
	v_cvt_pk_bf16_f32 v3, v4, v5
	ds_read2_b32 v[4:5], v12 offset0:4 offset1:69
	s_and_b32 s1, s1, 0x3fc0
	s_waitcnt lgkmcnt(0)
	v_cvt_pk_bf16_f32 v4, v4, v5
	v_or_b32_e32 v5, s0, v80
	s_add_i32 s8, s1, 0xffffd240
	v_lshlrev_b32_e32 v14, 11, v5
	v_lshl_add_u64 v[8:9], s[8:9], 1, v[36:37]
	ds_read2_b32 v[6:7], v12 offset0:134 offset1:199
	s_waitcnt lgkmcnt(0)
	v_cvt_pk_bf16_f32 v5, v6, v7
	v_lshl_add_u64 v[10:11], v[8:9], 0, v[14:15]
	ds_read2_b32 v[6:7], v81 offset0:8 offset1:73
	global_store_dwordx4 v[10:11], v[2:5], off
	v_or_b32_e32 v10, s0, v82
	v_lshlrev_b32_e32 v14, 11, v10
	s_waitcnt lgkmcnt(0)
	v_cvt_pk_bf16_f32 v2, v6, v7
	ds_read2_b32 v[4:5], v81 offset0:138 offset1:203
	s_waitcnt lgkmcnt(0)
	v_cvt_pk_bf16_f32 v3, v4, v5
	ds_read2_b32 v[4:5], v12 offset0:12 offset1:77
	s_waitcnt lgkmcnt(0)
	v_cvt_pk_bf16_f32 v4, v4, v5
	ds_read2_b32 v[6:7], v12 offset0:142 offset1:207
	s_waitcnt lgkmcnt(0)
	v_cvt_pk_bf16_f32 v5, v6, v7
	v_lshl_add_u64 v[10:11], v[8:9], 0, v[14:15]
	ds_read2_b32 v[6:7], v81 offset0:16 offset1:81
	global_store_dwordx4 v[10:11], v[2:5], off
	v_or_b32_e32 v10, s0, v83
	v_lshlrev_b32_e32 v14, 11, v10
	s_waitcnt lgkmcnt(0)
	v_cvt_pk_bf16_f32 v2, v6, v7
	ds_read2_b32 v[4:5], v81 offset0:146 offset1:211
	s_waitcnt lgkmcnt(0)
	v_cvt_pk_bf16_f32 v3, v4, v5
	ds_read2_b32 v[4:5], v12 offset0:20 offset1:85
	s_waitcnt lgkmcnt(0)
	v_cvt_pk_bf16_f32 v4, v4, v5
	ds_read2_b32 v[6:7], v12 offset0:150 offset1:215
	s_waitcnt lgkmcnt(0)
	v_cvt_pk_bf16_f32 v5, v6, v7
	v_lshl_add_u64 v[10:11], v[8:9], 0, v[14:15]
	ds_read2_b32 v[6:7], v81 offset0:24 offset1:89
	global_store_dwordx4 v[10:11], v[2:5], off
	v_or_b32_e32 v10, s0, v84
	v_lshlrev_b32_e32 v14, 11, v10
	s_waitcnt lgkmcnt(0)
	v_cvt_pk_bf16_f32 v2, v6, v7
	ds_read2_b32 v[4:5], v81 offset0:154 offset1:219
	s_waitcnt lgkmcnt(0)
	v_cvt_pk_bf16_f32 v3, v4, v5
	ds_read2_b32 v[4:5], v12 offset0:28 offset1:93
	s_waitcnt lgkmcnt(0)
	v_cvt_pk_bf16_f32 v4, v4, v5
	ds_read2_b32 v[6:7], v12 offset0:158 offset1:223
	s_waitcnt lgkmcnt(0)
	v_cvt_pk_bf16_f32 v5, v6, v7
	v_lshl_add_u64 v[10:11], v[8:9], 0, v[14:15]
	ds_read2_b32 v[6:7], v81 offset0:32 offset1:97
	global_store_dwordx4 v[10:11], v[2:5], off
	v_or_b32_e32 v10, s0, v85
	v_lshlrev_b32_e32 v14, 11, v10
	s_waitcnt lgkmcnt(0)
	v_cvt_pk_bf16_f32 v2, v6, v7
	ds_read2_b32 v[4:5], v81 offset0:162 offset1:227
	s_waitcnt lgkmcnt(0)
	v_cvt_pk_bf16_f32 v3, v4, v5
	ds_read2_b32 v[4:5], v12 offset0:36 offset1:101
	s_waitcnt lgkmcnt(0)
	v_cvt_pk_bf16_f32 v4, v4, v5
	ds_read2_b32 v[6:7], v12 offset0:166 offset1:231
	s_waitcnt lgkmcnt(0)
	v_cvt_pk_bf16_f32 v5, v6, v7
	v_lshl_add_u64 v[10:11], v[8:9], 0, v[14:15]
	ds_read2_b32 v[6:7], v81 offset0:40 offset1:105
	global_store_dwordx4 v[10:11], v[2:5], off
	v_or_b32_e32 v10, s0, v86
	v_lshlrev_b32_e32 v14, 11, v10
	s_waitcnt lgkmcnt(0)
	v_cvt_pk_bf16_f32 v2, v6, v7
	ds_read2_b32 v[4:5], v81 offset0:170 offset1:235
	s_waitcnt lgkmcnt(0)
	v_cvt_pk_bf16_f32 v3, v4, v5
	ds_read2_b32 v[4:5], v12 offset0:44 offset1:109
	s_waitcnt lgkmcnt(0)
	v_cvt_pk_bf16_f32 v4, v4, v5
	ds_read2_b32 v[6:7], v12 offset0:174 offset1:239
	s_waitcnt lgkmcnt(0)
	v_cvt_pk_bf16_f32 v5, v6, v7
	v_lshl_add_u64 v[10:11], v[8:9], 0, v[14:15]
	ds_read2_b32 v[6:7], v81 offset0:48 offset1:113
	global_store_dwordx4 v[10:11], v[2:5], off
	v_or_b32_e32 v10, s0, v87
	v_lshlrev_b32_e32 v14, 11, v10
	s_waitcnt lgkmcnt(0)
	v_cvt_pk_bf16_f32 v2, v6, v7
	ds_read2_b32 v[4:5], v81 offset0:178 offset1:243
	s_waitcnt lgkmcnt(0)
	v_cvt_pk_bf16_f32 v3, v4, v5
	ds_read2_b32 v[4:5], v12 offset0:52 offset1:117
	s_waitcnt lgkmcnt(0)
	v_cvt_pk_bf16_f32 v4, v4, v5
	ds_read2_b32 v[6:7], v12 offset0:182 offset1:247
	s_waitcnt lgkmcnt(0)
	v_cvt_pk_bf16_f32 v5, v6, v7
	v_lshl_add_u64 v[10:11], v[8:9], 0, v[14:15]
	ds_read2_b32 v[6:7], v81 offset0:56 offset1:121
	global_store_dwordx4 v[10:11], v[2:5], off
	s_waitcnt lgkmcnt(0)
	s_nop 0
	v_cvt_pk_bf16_f32 v2, v6, v7
	ds_read2_b32 v[4:5], v81 offset0:186 offset1:251
	s_waitcnt lgkmcnt(0)
	v_cvt_pk_bf16_f32 v3, v4, v5
	ds_read2_b32 v[4:5], v12 offset0:60 offset1:125
	s_waitcnt lgkmcnt(0)
	v_cvt_pk_bf16_f32 v4, v4, v5
	v_or_b32_e32 v5, s0, v88
	ds_read2_b32 v[6:7], v12 offset0:190 offset1:255
	v_lshlrev_b32_e32 v14, 11, v5
	s_waitcnt lgkmcnt(0)
	v_cvt_pk_bf16_f32 v5, v6, v7
	v_lshl_add_u64 v[6:7], v[8:9], 0, v[14:15]
	global_store_dwordx4 v[6:7], v[2:5], off
	s_waitcnt lgkmcnt(0)

.LBB0_107:
	v_lshl_add_u64 v[64:65], v[10:11], 0, s[0:1]
	v_add_co_u32_e32 v74, vcc, 0xf000, v64
	v_lshl_add_u64 v[62:63], v[12:13], 0, s[0:1]
	s_nop 0
	v_addc_co_u32_e32 v75, vcc, 0, v65, vcc
	v_add_co_u32_e32 v76, vcc, 0x1f000, v64
	v_lshl_add_u64 v[66:67], v[8:9], 0, s[0:1]
	s_nop 0
	v_addc_co_u32_e32 v77, vcc, 0, v65, vcc
	v_lshl_add_u64 v[68:69], v[6:7], 0, s[0:1]
	v_lshl_add_u64 v[70:71], v[4:5], 0, s[0:1]
	v_lshl_add_u64 v[72:73], v[2:3], 0, s[0:1]
	v_add_co_u32_e32 v64, vcc, 0x2e000, v64
	global_load_dwordx2 v[62:63], v[62:63], off
	s_nop 0
	global_load_dwordx2 v[66:67], v[66:67], off
	s_nop 0
	global_load_dwordx2 v[68:69], v[68:69], off
	s_nop 0
	global_load_dwordx2 v[70:71], v[70:71], off
	s_nop 0
	global_load_dwordx2 v[72:73], v[72:73], off
	v_addc_co_u32_e32 v65, vcc, 0, v65, vcc
	global_load_dwordx2 v[74:75], v[74:75], off offset:2560
	s_nop 0
	global_load_dwordx2 v[76:77], v[76:77], off offset:1024
	s_nop 0
	global_load_dwordx2 v[64:65], v[64:65], off offset:3584
	s_add_u32 s0, s0, 0x7d000
	s_addc_u32 s1, s1, 0
	v_lshl_add_u64 v[164:165], v[10:11], 0, s[0:1]
	v_add_co_u32_e32 v160, vcc, 0xf000, v164
	v_lshl_add_u64 v[150:151], v[12:13], 0, s[0:1]
	s_nop 0
	v_addc_co_u32_e32 v161, vcc, 0, v165, vcc
	v_add_co_u32_e32 v162, vcc, 0x1f000, v164
	v_lshl_add_u64 v[152:153], v[8:9], 0, s[0:1]
	s_nop 0
	v_addc_co_u32_e32 v163, vcc, 0, v165, vcc
	v_lshl_add_u64 v[154:155], v[6:7], 0, s[0:1]
	v_lshl_add_u64 v[156:157], v[4:5], 0, s[0:1]
	v_lshl_add_u64 v[158:159], v[2:3], 0, s[0:1]
	v_add_co_u32_e32 v164, vcc, 0x2e000, v164
	global_load_dwordx2 v[150:151], v[150:151], off
	s_nop 0
	global_load_dwordx2 v[152:153], v[152:153], off
	s_nop 0
	global_load_dwordx2 v[154:155], v[154:155], off
	s_nop 0
	global_load_dwordx2 v[156:157], v[156:157], off
	s_nop 0
	global_load_dwordx2 v[158:159], v[158:159], off
	v_addc_co_u32_e32 v165, vcc, 0, v165, vcc
	global_load_dwordx2 v[160:161], v[160:161], off offset:2560
	s_nop 0
	global_load_dwordx2 v[162:163], v[162:163], off offset:1024
	s_nop 0
	global_load_dwordx2 v[164:165], v[164:165], off offset:3584
	s_add_u32 s0, s0, 0x7d000
	s_addc_u32 s1, s1, 0
	v_lshl_add_u64 v[180:181], v[10:11], 0, s[0:1]
	v_add_co_u32_e32 v176, vcc, 0xf000, v180
	v_lshl_add_u64 v[166:167], v[12:13], 0, s[0:1]
	s_nop 0
	v_addc_co_u32_e32 v177, vcc, 0, v181, vcc
	v_add_co_u32_e32 v178, vcc, 0x1f000, v180
	v_lshl_add_u64 v[168:169], v[8:9], 0, s[0:1]
	s_nop 0
	v_addc_co_u32_e32 v179, vcc, 0, v181, vcc
	v_lshl_add_u64 v[170:171], v[6:7], 0, s[0:1]
	v_lshl_add_u64 v[172:173], v[4:5], 0, s[0:1]
	v_lshl_add_u64 v[174:175], v[2:3], 0, s[0:1]
	v_add_co_u32_e32 v180, vcc, 0x2e000, v180
	global_load_dwordx2 v[166:167], v[166:167], off
	s_nop 0
	global_load_dwordx2 v[168:169], v[168:169], off
	s_nop 0
	global_load_dwordx2 v[170:171], v[170:171], off
	s_nop 0
	global_load_dwordx2 v[172:173], v[172:173], off
	s_nop 0
	global_load_dwordx2 v[174:175], v[174:175], off
	v_addc_co_u32_e32 v181, vcc, 0, v181, vcc
	global_load_dwordx2 v[176:177], v[176:177], off offset:2560
	s_nop 0
	global_load_dwordx2 v[178:179], v[178:179], off offset:1024
	s_nop 0
	global_load_dwordx2 v[180:181], v[180:181], off offset:3584
	s_add_u32 s0, s0, 0x7d000
	s_addc_u32 s1, s1, 0
	v_lshl_add_u64 v[196:197], v[10:11], 0, s[0:1]
	v_add_co_u32_e32 v192, vcc, 0xf000, v196
	v_lshl_add_u64 v[182:183], v[12:13], 0, s[0:1]
	s_nop 0
	v_addc_co_u32_e32 v193, vcc, 0, v197, vcc
	v_add_co_u32_e32 v194, vcc, 0x1f000, v196
	v_lshl_add_u64 v[184:185], v[8:9], 0, s[0:1]
	s_nop 0
	v_addc_co_u32_e32 v195, vcc, 0, v197, vcc
	v_lshl_add_u64 v[186:187], v[6:7], 0, s[0:1]
	v_lshl_add_u64 v[188:189], v[4:5], 0, s[0:1]
	v_lshl_add_u64 v[190:191], v[2:3], 0, s[0:1]
	v_add_co_u32_e32 v196, vcc, 0x2e000, v196
	global_load_dwordx2 v[182:183], v[182:183], off
	s_nop 0
	global_load_dwordx2 v[184:185], v[184:185], off
	s_nop 0
	global_load_dwordx2 v[186:187], v[186:187], off
	s_nop 0
	global_load_dwordx2 v[188:189], v[188:189], off
	s_nop 0
	global_load_dwordx2 v[190:191], v[190:191], off
	v_addc_co_u32_e32 v197, vcc, 0, v197, vcc
	global_load_dwordx2 v[192:193], v[192:193], off offset:2560
	s_nop 0
	global_load_dwordx2 v[194:195], v[194:195], off offset:1024
	s_nop 0
	global_load_dwordx2 v[196:197], v[196:197], off offset:3584
	s_add_u32 s0, s0, 0x7d000
	s_addc_u32 s1, s1, 0
	v_add_u32_e32 v108, 0x410, v14
	v_add_u32_e32 v109, 0x618, v14
	v_add_u32_e32 v110, 0x820, v14
	v_add_u32_e32 v111, 0xa28, v14
	v_add_u32_e32 v112, 0xc30, v14
	v_add_u32_e32 v113, 0xe38, v14
	s_waitcnt vmcnt(31)
	ds_write2_b32 v14, v62, v63 offset1:1
	s_waitcnt vmcnt(30)
	ds_write2_b32 v110, v66, v67 offset1:1
	s_waitcnt vmcnt(29)
	ds_write2_b32 v111, v68, v69 offset1:1
	s_waitcnt vmcnt(28)
	ds_write2_b32 v112, v70, v71 offset1:1
	s_waitcnt vmcnt(27)
	ds_write2_b32 v113, v72, v73 offset1:1
	s_waitcnt vmcnt(26)
	ds_write2_b32 v14, v74, v75 offset0:130 offset1:131
	v_add_u32_e32 v14, 0x1040, v14
	s_waitcnt vmcnt(25)
	ds_write2_b32 v108, v76, v77 offset1:1
	s_waitcnt vmcnt(24)
	ds_write2_b32 v109, v64, v65 offset1:1
	v_add_u32_e32 v108, 0x410, v14
	v_add_u32_e32 v109, 0x618, v14
	v_add_u32_e32 v110, 0x820, v14
	v_add_u32_e32 v111, 0xa28, v14
	v_add_u32_e32 v112, 0xc30, v14
	v_add_u32_e32 v113, 0xe38, v14
	s_waitcnt vmcnt(23)
	ds_write2_b32 v14, v150, v151 offset1:1
	s_waitcnt vmcnt(22)
	ds_write2_b32 v110, v152, v153 offset1:1
	s_waitcnt vmcnt(21)
	ds_write2_b32 v111, v154, v155 offset1:1
	s_waitcnt vmcnt(20)
	ds_write2_b32 v112, v156, v157 offset1:1
	s_waitcnt vmcnt(19)
	ds_write2_b32 v113, v158, v159 offset1:1
	s_waitcnt vmcnt(18)
	ds_write2_b32 v14, v160, v161 offset0:130 offset1:131
	v_add_u32_e32 v14, 0x1040, v14
	s_waitcnt vmcnt(17)
	ds_write2_b32 v108, v162, v163 offset1:1
	s_waitcnt vmcnt(16)
	ds_write2_b32 v109, v164, v165 offset1:1
	v_add_u32_e32 v108, 0x410, v14
	v_add_u32_e32 v109, 0x618, v14
	v_add_u32_e32 v110, 0x820, v14
	v_add_u32_e32 v111, 0xa28, v14
	v_add_u32_e32 v112, 0xc30, v14
	v_add_u32_e32 v113, 0xe38, v14
	s_waitcnt vmcnt(15)
	ds_write2_b32 v14, v166, v167 offset1:1
	s_waitcnt vmcnt(14)
	ds_write2_b32 v110, v168, v169 offset1:1
	s_waitcnt vmcnt(13)
	ds_write2_b32 v111, v170, v171 offset1:1
	s_waitcnt vmcnt(12)
	ds_write2_b32 v112, v172, v173 offset1:1
	s_waitcnt vmcnt(11)
	ds_write2_b32 v113, v174, v175 offset1:1
	s_waitcnt vmcnt(10)
	ds_write2_b32 v14, v176, v177 offset0:130 offset1:131
	v_add_u32_e32 v14, 0x1040, v14
	s_waitcnt vmcnt(9)
	ds_write2_b32 v108, v178, v179 offset1:1
	s_waitcnt vmcnt(8)
	ds_write2_b32 v109, v180, v181 offset1:1
	v_add_u32_e32 v108, 0x410, v14
	v_add_u32_e32 v109, 0x618, v14
	v_add_u32_e32 v110, 0x820, v14
	v_add_u32_e32 v111, 0xa28, v14
	v_add_u32_e32 v112, 0xc30, v14
	v_add_u32_e32 v113, 0xe38, v14
	s_waitcnt vmcnt(7)
	ds_write2_b32 v14, v182, v183 offset1:1
	s_waitcnt vmcnt(6)
	ds_write2_b32 v110, v184, v185 offset1:1
	s_waitcnt vmcnt(5)
	ds_write2_b32 v111, v186, v187 offset1:1
	s_waitcnt vmcnt(4)
	ds_write2_b32 v112, v188, v189 offset1:1
	s_waitcnt vmcnt(3)
	ds_write2_b32 v113, v190, v191 offset1:1
	s_waitcnt vmcnt(2)
	ds_write2_b32 v14, v192, v193 offset0:130 offset1:131
	v_add_u32_e32 v14, 0x1040, v14
	s_waitcnt vmcnt(1)
	ds_write2_b32 v108, v194, v195 offset1:1
	s_waitcnt vmcnt(0)
	ds_write2_b32 v109, v196, v197 offset1:1
	s_and_b32 s0, 0xffff, s4
	s_cmp_gt_u32 s0, 60
	s_waitcnt lgkmcnt(0)
	s_cselect_b32 s0, 0xc0, 0
	s_and_b32 s1, 0xffff, s3
	ds_read2_b32 v[2:3], v81 offset1:65
	s_and_b32 s2, 0xffff, s2
	s_add_i32 s0, s0, s1
	s_waitcnt lgkmcnt(0)
	v_cvt_pk_bf16_f32 v2, v2, v3
	ds_read2_b32 v[4:5], v81 offset0:130 offset1:195
	v_add_u32_e32 v12, 0x400, v81
	s_lshl_b32 s8, s2, 1
	v_or_b32_e32 v10, s0, v80
	s_waitcnt lgkmcnt(0)
	v_cvt_pk_bf16_f32 v3, v4, v5
	ds_read2_b32 v[4:5], v12 offset0:4 offset1:69
	v_lshl_add_u64 v[8:9], v[44:45], 0, s[8:9]
	v_lshlrev_b32_e32 v14, 12, v10
	s_waitcnt lgkmcnt(0)
	v_cvt_pk_bf16_f32 v4, v4, v5
	ds_read2_b32 v[6:7], v12 offset0:134 offset1:199
	s_waitcnt lgkmcnt(0)
	v_cvt_pk_bf16_f32 v5, v6, v7
	v_lshl_add_u64 v[10:11], v[8:9], 0, v[14:15]
	ds_read2_b32 v[6:7], v81 offset0:8 offset1:73
	global_store_dwordx4 v[10:11], v[2:5], off
	v_or_b32_e32 v10, s0, v82
	v_lshlrev_b32_e32 v14, 12, v10
	s_waitcnt lgkmcnt(0)
	v_cvt_pk_bf16_f32 v2, v6, v7
	ds_read2_b32 v[4:5], v81 offset0:138 offset1:203
	s_waitcnt lgkmcnt(0)
	v_cvt_pk_bf16_f32 v3, v4, v5
	ds_read2_b32 v[4:5], v12 offset0:12 offset1:77
	s_waitcnt lgkmcnt(0)
	v_cvt_pk_bf16_f32 v4, v4, v5
	ds_read2_b32 v[6:7], v12 offset0:142 offset1:207
	s_waitcnt lgkmcnt(0)
	v_cvt_pk_bf16_f32 v5, v6, v7
	v_lshl_add_u64 v[10:11], v[8:9], 0, v[14:15]
	ds_read2_b32 v[6:7], v81 offset0:16 offset1:81
	global_store_dwordx4 v[10:11], v[2:5], off
	v_or_b32_e32 v10, s0, v83
	v_lshlrev_b32_e32 v14, 12, v10
	s_waitcnt lgkmcnt(0)
	v_cvt_pk_bf16_f32 v2, v6, v7
	ds_read2_b32 v[4:5], v81 offset0:146 offset1:211
	s_waitcnt lgkmcnt(0)
	v_cvt_pk_bf16_f32 v3, v4, v5
	ds_read2_b32 v[4:5], v12 offset0:20 offset1:85
	s_waitcnt lgkmcnt(0)
	v_cvt_pk_bf16_f32 v4, v4, v5
	ds_read2_b32 v[6:7], v12 offset0:150 offset1:215
	s_waitcnt lgkmcnt(0)
	v_cvt_pk_bf16_f32 v5, v6, v7
	v_lshl_add_u64 v[10:11], v[8:9], 0, v[14:15]
	ds_read2_b32 v[6:7], v81 offset0:24 offset1:89
	global_store_dwordx4 v[10:11], v[2:5], off
	v_or_b32_e32 v10, s0, v84
	v_lshlrev_b32_e32 v14, 12, v10
	s_waitcnt lgkmcnt(0)
	v_cvt_pk_bf16_f32 v2, v6, v7
	ds_read2_b32 v[4:5], v81 offset0:154 offset1:219
	s_waitcnt lgkmcnt(0)
	v_cvt_pk_bf16_f32 v3, v4, v5
	ds_read2_b32 v[4:5], v12 offset0:28 offset1:93
	s_waitcnt lgkmcnt(0)
	v_cvt_pk_bf16_f32 v4, v4, v5
	ds_read2_b32 v[6:7], v12 offset0:158 offset1:223
	s_waitcnt lgkmcnt(0)
	v_cvt_pk_bf16_f32 v5, v6, v7
	v_lshl_add_u64 v[10:11], v[8:9], 0, v[14:15]
	ds_read2_b32 v[6:7], v81 offset0:32 offset1:97
	global_store_dwordx4 v[10:11], v[2:5], off
	v_or_b32_e32 v10, s0, v85
	v_lshlrev_b32_e32 v14, 12, v10
	s_waitcnt lgkmcnt(0)
	v_cvt_pk_bf16_f32 v2, v6, v7
	ds_read2_b32 v[4:5], v81 offset0:162 offset1:227
	s_waitcnt lgkmcnt(0)
	v_cvt_pk_bf16_f32 v3, v4, v5
	ds_read2_b32 v[4:5], v12 offset0:36 offset1:101
	s_waitcnt lgkmcnt(0)
	v_cvt_pk_bf16_f32 v4, v4, v5
	ds_read2_b32 v[6:7], v12 offset0:166 offset1:231
	s_waitcnt lgkmcnt(0)
	v_cvt_pk_bf16_f32 v5, v6, v7
	v_lshl_add_u64 v[10:11], v[8:9], 0, v[14:15]
	ds_read2_b32 v[6:7], v81 offset0:40 offset1:105
	global_store_dwordx4 v[10:11], v[2:5], off
	v_or_b32_e32 v10, s0, v86
	v_lshlrev_b32_e32 v14, 12, v10
	s_waitcnt lgkmcnt(0)
	v_cvt_pk_bf16_f32 v2, v6, v7
	ds_read2_b32 v[4:5], v81 offset0:170 offset1:235
	s_waitcnt lgkmcnt(0)
	v_cvt_pk_bf16_f32 v3, v4, v5
	ds_read2_b32 v[4:5], v12 offset0:44 offset1:109
	s_waitcnt lgkmcnt(0)
	v_cvt_pk_bf16_f32 v4, v4, v5
	ds_read2_b32 v[6:7], v12 offset0:174 offset1:239
	s_waitcnt lgkmcnt(0)
	v_cvt_pk_bf16_f32 v5, v6, v7
	v_lshl_add_u64 v[10:11], v[8:9], 0, v[14:15]
	ds_read2_b32 v[6:7], v81 offset0:48 offset1:113
	global_store_dwordx4 v[10:11], v[2:5], off
	v_or_b32_e32 v10, s0, v87
	v_lshlrev_b32_e32 v14, 12, v10
	s_waitcnt lgkmcnt(0)
	v_cvt_pk_bf16_f32 v2, v6, v7
	ds_read2_b32 v[4:5], v81 offset0:178 offset1:243
	s_waitcnt lgkmcnt(0)
	v_cvt_pk_bf16_f32 v3, v4, v5
	ds_read2_b32 v[4:5], v12 offset0:52 offset1:117
	s_waitcnt lgkmcnt(0)
	v_cvt_pk_bf16_f32 v4, v4, v5
	ds_read2_b32 v[6:7], v12 offset0:182 offset1:247
	s_waitcnt lgkmcnt(0)
	v_cvt_pk_bf16_f32 v5, v6, v7
	v_lshl_add_u64 v[10:11], v[8:9], 0, v[14:15]
	ds_read2_b32 v[6:7], v81 offset0:56 offset1:121
	global_store_dwordx4 v[10:11], v[2:5], off
	s_waitcnt lgkmcnt(0)
	s_nop 0
	v_cvt_pk_bf16_f32 v2, v6, v7
	ds_read2_b32 v[4:5], v81 offset0:186 offset1:251
	s_waitcnt lgkmcnt(0)
	v_cvt_pk_bf16_f32 v3, v4, v5
	ds_read2_b32 v[4:5], v12 offset0:60 offset1:125
	s_waitcnt lgkmcnt(0)
	v_cvt_pk_bf16_f32 v4, v4, v5
	v_or_b32_e32 v5, s0, v88
	ds_read2_b32 v[6:7], v12 offset0:190 offset1:255
	v_lshlrev_b32_e32 v14, 12, v5
	s_waitcnt lgkmcnt(0)
	v_cvt_pk_bf16_f32 v5, v6, v7
	v_lshl_add_u64 v[6:7], v[8:9], 0, v[14:15]
	global_store_dwordx4 v[6:7], v[2:5], off
	s_waitcnt lgkmcnt(0)
